# attention K/V tile DMA uses SGPR base plus 32-bit lane offsets (scalar address arithmetic instead of 64-bit VALU adds)
# speedup vs baseline: 1.0239x; 1.0083x over previous
.LBB0_625:
	s_add_u32 s4, s0, s14
	s_addc_u32 s5, s1, s15
	global_load_dwordx4 v[4:7], v193, s[4:5] offset:48
	global_load_dwordx4 v[8:11], v193, s[4:5] offset:32
	global_load_dwordx4 v[12:15], v193, s[4:5] offset:16
	global_load_dwordx4 v[16:19], v193, s[4:5]
	global_load_dwordx4 v[20:23], v193, s[4:5] offset:304
	global_load_dwordx4 v[24:27], v193, s[4:5] offset:288
	global_load_dwordx4 v[28:31], v193, s[4:5] offset:272
	global_load_dwordx4 v[32:35], v193, s[4:5] offset:256
	global_load_dwordx4 v[36:39], v193, s[4:5] offset:560
	global_load_dwordx4 v[40:43], v193, s[4:5] offset:544
	global_load_dwordx4 v[44:47], v193, s[4:5] offset:528
	global_load_dwordx4 v[48:51], v193, s[4:5] offset:512
	global_load_dwordx4 v[52:55], v193, s[4:5] offset:816
	global_load_dwordx4 v[56:59], v193, s[4:5] offset:800
	global_load_dwordx4 v[60:63], v193, s[4:5] offset:784
	global_load_dwordx4 v[64:67], v193, s[4:5] offset:768
	s_add_u32 s14, s14, 64
	s_addc_u32 s15, s15, 0
	s_cmpk_eq_i32 s14, 0x100
	s_waitcnt vmcnt(12)
	v_mov_b32_e32 v68, v16
	v_mov_b32_e32 v16, v18
	s_waitcnt vmcnt(9)
	v_mov_b32_e32 v18, v28
	s_waitcnt vmcnt(8)
	v_mov_b32_e32 v70, v32
	v_mov_b32_e32 v32, v34
	s_waitcnt vmcnt(4)
	v_mov_b32_e32 v69, v48
	v_mov_b32_e32 v48, v17
	v_mov_b32_e32 v17, v50
	v_mov_b32_e32 v50, v19
	s_waitcnt vmcnt(0)
	v_mov_b32_e32 v71, v64
	v_pk_fma_f32 v[0:1], v[68:69], v[70:71], v[0:1]
	v_mov_b32_e32 v64, v33
	v_pk_fma_f32 v[0:1], v[48:49], v[64:65], v[0:1]
	v_mov_b32_e32 v33, v66
	v_pk_fma_f32 v[0:1], v[16:17], v[32:33], v[0:1]
	v_mov_b32_e32 v66, v35
	v_pk_fma_f32 v[0:1], v[50:51], v[66:67], v[0:1]
	v_mov_b32_e32 v16, v12
	v_mov_b32_e32 v17, v44
	v_mov_b32_e32 v19, v60
	v_pk_fma_f32 v[0:1], v[16:17], v[18:19], v[0:1]
	v_mov_b32_e32 v44, v13
	v_mov_b32_e32 v60, v29
	v_pk_fma_f32 v[0:1], v[44:45], v[60:61], v[0:1]
	v_mov_b32_e32 v12, v14
	v_mov_b32_e32 v13, v46
	v_mov_b32_e32 v16, v30
	v_mov_b32_e32 v17, v62
	v_pk_fma_f32 v[0:1], v[12:13], v[16:17], v[0:1]
	v_mov_b32_e32 v46, v15
	v_mov_b32_e32 v62, v31
	v_pk_fma_f32 v[0:1], v[46:47], v[62:63], v[0:1]
	v_mov_b32_e32 v12, v8
	v_mov_b32_e32 v13, v40
	v_mov_b32_e32 v14, v24
	v_mov_b32_e32 v15, v56
	v_pk_fma_f32 v[0:1], v[12:13], v[14:15], v[0:1]
	v_mov_b32_e32 v40, v9
	v_mov_b32_e32 v56, v25
	v_pk_fma_f32 v[0:1], v[40:41], v[56:57], v[0:1]
	v_mov_b32_e32 v8, v10
	v_mov_b32_e32 v9, v42
	v_mov_b32_e32 v12, v26
	v_mov_b32_e32 v13, v58
	v_pk_fma_f32 v[0:1], v[8:9], v[12:13], v[0:1]
	v_mov_b32_e32 v42, v11
	v_mov_b32_e32 v58, v27
	v_pk_fma_f32 v[0:1], v[42:43], v[58:59], v[0:1]
	v_mov_b32_e32 v8, v4
	v_mov_b32_e32 v9, v36
	v_mov_b32_e32 v10, v20
	v_mov_b32_e32 v11, v52
	v_pk_fma_f32 v[0:1], v[8:9], v[10:11], v[0:1]
	v_mov_b32_e32 v36, v5
	v_mov_b32_e32 v52, v21
	v_pk_fma_f32 v[0:1], v[36:37], v[52:53], v[0:1]
	v_mov_b32_e32 v4, v6
	v_mov_b32_e32 v5, v38
	v_mov_b32_e32 v8, v22
	v_mov_b32_e32 v9, v54
	v_pk_fma_f32 v[0:1], v[4:5], v[8:9], v[0:1]
	v_mov_b32_e32 v38, v7
	v_mov_b32_e32 v54, v23
	v_pk_fma_f32 v[0:1], v[38:39], v[54:55], v[0:1]
	s_cbranch_scc0 .LBB0_625
	v_readfirstlane_b32 s0, v3
	s_cmpk_gt_i32 s0, 0x3ff
	s_cbranch_scc1 .LBB0_654
	v_readlane_b32 s14, v252, 1
	s_mov_b32 s1, 0x3fb8aa3b
	s_mov_b32 s4, 0xc2ce8ed0
	v_cvt_f32_u32_e32 v3, s14
	s_mov_b32 s5, 0x42b17218
	s_add_u32 s6, s6, 0x5720000
	s_addc_u32 s7, s7, 0
	v_mul_f32_e32 v3, 0xbe99999a, v3
	v_mul_f32_e32 v4, 0x3fb8aa3b, v3
	v_fma_f32 v5, v3, s1, -v4
	v_rndne_f32_e32 v6, v4
	v_fmac_f32_e32 v5, 0x32a5705f, v3
	v_sub_f32_e32 v4, v4, v6
	v_add_f32_e32 v4, v4, v5
	v_cvt_i32_f32_e32 v6, v6
	v_exp_f32_e32 v4, v4
	v_cmp_ngt_f32_e32 vcc, s4, v3
	s_add_u32 s10, s10, 0x9b20000
	s_addc_u32 s11, s11, 0
	v_ldexp_f32 v4, v4, v6
	v_cndmask_b32_e32 v4, 0, v4, vcc
	v_cmp_nlt_f32_e32 vcc, s5, v3
	v_readlane_b32 s15, v252, 2
	s_add_u32 s12, s12, 0x3700000
	v_cndmask_b32_e32 v3, v241, v4, vcc
	v_mul_f32_e32 v4, 0x3fb8aa3b, v0
	v_rndne_f32_e32 v5, v4
	v_sub_f32_e32 v6, v4, v5
	v_fma_f32 v4, v0, s1, -v4
	v_fmac_f32_e32 v4, 0x32a5705f, v0
	v_add_f32_e32 v4, v6, v4
	v_exp_f32_e32 v4, v4
	v_cvt_i32_f32_e32 v5, v5
	v_cmp_ngt_f32_e32 vcc, s4, v0
	s_addc_u32 s13, s13, 0
	s_ashr_i32 s28, s2, 8
	v_ldexp_f32 v4, v4, v5
	v_mul_f32_e32 v5, 0x3fb8aa3b, v1
	v_rndne_f32_e32 v6, v5
	v_sub_f32_e32 v7, v5, v6
	v_fma_f32 v5, v1, s1, -v5
	v_fmac_f32_e32 v5, 0x32a5705f, v1
	v_add_f32_e32 v5, v7, v5
	v_exp_f32_e32 v5, v5
	v_cvt_i32_f32_e32 v6, v6
	v_cndmask_b32_e32 v4, 0, v4, vcc
	v_cmp_nlt_f32_e32 vcc, s5, v0
	s_ashr_i32 s16, s2, 6
	v_fmamk_f32 v3, v3, 0xbf19999a, v239
	v_cndmask_b32_e32 v0, v241, v4, vcc
	v_ldexp_f32 v4, v5, v6
	v_cmp_ngt_f32_e32 vcc, s4, v1
	v_sub_f32_e32 v176, 1.0, v3
	v_and_b32_e32 v7, 63, v2
	v_cndmask_b32_e32 v4, 0, v4, vcc
	v_cmp_nlt_f32_e32 vcc, s5, v1
	s_lshl_b64 s[4:5], s[14:15], 9
	s_add_u32 s26, s42, s4
	s_addc_u32 s27, s43, s5
	s_lshl_b32 s1, s0, 1
	s_and_b32 s1, s1, 14
	s_ashr_i32 s4, s0, 7
	s_lshl_b32 s14, s28, 6
	s_lshl_b32 s5, s16, 10
	v_cndmask_b32_e32 v1, v241, v4, vcc
	s_and_b32 s30, s16, 3
	s_add_i32 s1, s1, s4
	s_lshr_b32 s4, s0, 3
	s_ashr_i32 s15, s14, 31
	s_add_i32 s5, s5, 0
	v_sub_f32_e32 v0, v0, v1
	s_cmpk_lt_u32 s2, 0x100
	v_add_f32_e32 v177, v3, v0
	v_lshrrev_b32_e32 v3, 1, v2
	v_lshlrev_b32_e32 v0, 1, v2
	s_cselect_b64 s[16:17], -1, 0
	s_lshl_b32 s2, s28, 13
	v_and_b32_e32 v0, 8, v0
	v_and_b32_e32 v4, 19, v2
	v_and_b32_e32 v6, 4, v3
	s_add_i32 s2, s2, 0
	v_and_b32_e32 v1, 31, v2
	v_or3_b32 v4, v0, v4, v6
	s_cmp_eq_u32 s28, 1
	v_lshl_or_b32 v178, s30, 5, v1
	v_lshl_add_u32 v179, v4, 7, s2
	s_cselect_b64 s[28:29], -1, 0
	v_lshlrev_b32_e32 v1, 7, v1
	s_add_i32 s2, 0, 0x1c000
	v_add_u32_e32 v180, s2, v1
	s_lshl_b32 s2, s30, 14
	v_lshrrev_b32_e32 v6, 1, v4
	v_bfe_u32 v8, v2, 5, 1
	s_add_i32 s2, s2, 0
	v_lshl_add_u32 v181, v7, 2, s2
	v_bitop3_b32 v7, v6, v8, 7 bitop3:0x6c
	v_lshlrev_b32_e32 v182, 4, v7
	v_or_b32_e32 v7, 2, v8
	v_bitop3_b32 v7, v6, v7, 7 bitop3:0x6c
	v_lshlrev_b32_e32 v183, 4, v7
	v_or_b32_e32 v7, 4, v8
	v_lshrrev_b32_e32 v9, 4, v2
	v_bitop3_b32 v7, v6, v7, 7 bitop3:0x6c
	v_ashrrev_i32_e32 v160, 3, v2
	v_bfe_u32 v5, v2, 1, 3
	v_xor_b32_e32 v2, v9, v2
	v_lshlrev_b32_e32 v184, 4, v7
	v_or_b32_e32 v7, 6, v8
	v_bitop3_b32 v3, v8, v3, 7 bitop3:0x78
	v_lshlrev_b32_e32 v2, 3, v2
	v_bitop3_b32 v6, v6, v7, 7 bitop3:0x6c
	v_lshlrev_b32_e32 v187, 4, v3
	v_bitop3_b32 v3, v8, v5, 2 bitop3:0x36
	v_lshlrev_b32_e32 v0, 3, v8
	v_and_b32_e32 v2, 56, v2
	v_lshlrev_b32_e32 v4, 2, v8
	v_lshlrev_b32_e32 v192, 4, v8
	v_lshlrev_b32_e32 v185, 4, v6
	v_bitop3_b32 v6, v8, v5, 4 bitop3:0x36
	v_lshlrev_b32_e32 v188, 4, v3
	v_bitop3_b32 v3, v8, v5, 6 bitop3:0x36
	v_ashrrev_i32_e32 v161, 31, v160
	v_lshl_add_u64 v[162:163], s[26:27], 0, v[192:193]
	s_add_i32 s26, s5, 0x10000
	s_add_i32 s27, s5, 0x12000
	s_add_i32 s34, s5, 0x14000
	s_add_i32 s35, s5, 0x16000
	s_add_i32 s36, s5, 0x18000
	s_add_i32 s37, s5, 0x1a000
	s_add_i32 s44, s5, 0x1c000
	s_add_i32 s45, s5, 0x1e000
	v_lshlrev_b32_e32 v186, 4, v6
	v_lshlrev_b32_e32 v189, 4, v3
	v_add_u32_e32 v190, 0, v1
	s_mov_b32 s46, 0
	v_lshlrev_b32_e32 v192, 1, v0
	v_lshlrev_b32_e32 v164, 1, v2
	v_lshlrev_b32_e32 v166, 1, v4
	v_add_u32_e32 v182, v179, v182
	v_add_u32_e32 v183, v179, v183
	v_add_u32_e32 v184, v179, v184
	v_add_u32_e32 v185, v179, v185
	v_add_u32_e32 v187, v190, v187
	v_add_u32_e32 v188, v190, v188
	v_add_u32_e32 v186, v190, v186
	v_add_u32_e32 v189, v190, v189
	v_add_u32_e32 v187, 0x10000, v187
	v_add_u32_e32 v188, 0x10000, v188
	v_add_u32_e32 v186, 0x10000, v186
	v_add_u32_e32 v189, 0x10000, v189
	s_add_u32 s26, s6, 0x800
	s_addc_u32 s27, s7, 0
	s_mov_b32 s2, s0
	s_branch .LBB0_629

.LBB0_629:
	s_lshl_b32 s30, s46, 4
	s_add_i32 s38, s1, s30
	v_readlane_b32 s30, v253, 52
	s_ashr_i32 s39, s2, 4
	v_readlane_b32 s31, v253, 53
	s_and_b64 s[30:31], s[30:31], exec
	s_cselect_b32 s39, s38, s39
	s_cselect_b32 s2, s4, s2
	s_ashr_i32 s40, s39, 3
	s_and_b32 s38, s2, 15
	s_ashr_i32 s41, s40, 31
	s_lshl_b64 s[42:43], s[40:41], 11
	v_lshl_or_b32 v0, s38, 7, v178
	v_or_b32_e32 v168, s42, v0
	v_mov_b64_e32 v[0:1], s[6:7]
	s_movk_i32 s47, 0x1100
	s_lshl_b32 s2, s39, 7
	v_mad_u64_u32 v[2:3], s[30:31], v168, s47, v[0:1]
	s_and_b32 s2, s2, 0x380
	v_mad_i32_i24 v3, s43, v242, v3
	s_lshl_b32 s30, s2, 1
	s_mov_b32 s31, s3
	v_lshl_add_u64 v[2:3], v[2:3], 0, s[30:31]
	v_lshl_add_u64 v[2:3], s[14:15], 1, v[2:3]
	v_lshl_add_u64 v[2:3], v[2:3], 0, v[192:193]
	global_load_dwordx4 v[128:131], v[2:3], off
	global_load_dwordx4 v[132:135], v[2:3], off offset:32
	global_load_dwordx4 v[136:139], v[2:3], off offset:64
	global_load_dwordx4 v[140:143], v[2:3], off offset:96
	v_lshl_add_u64 v[2:3], s[42:43], 0, v[160:161]
	v_mov_b32_e32 v169, s43
	v_mad_u64_u32 v[0:1], s[42:43], v2, s47, v[0:1]
	v_mad_i32_i24 v1, v3, s47, v1
	v_lshl_add_u64 v[0:1], v[0:1], 0, s[30:31]
	v_mov_b32_e32 v165, v193
	v_lshl_add_u64 v[170:171], v[0:1], 0, v[164:165]
	v_add_u32_e32 v2, s2, v160
	v_mov_b64_e32 v[0:1], s[10:11]
	v_mad_i64_i32 v[0:1], s[42:43], v2, s73, v[0:1]
	s_lshl_b64 s[40:41], s[40:41], 12
	v_lshl_add_u64 v[0:1], v[0:1], 0, s[40:41]
	s_mul_i32 s2, s38, 0x88000
	v_lshl_add_u64 v[172:173], v[0:1], 0, v[164:165]
	s_lshl_b32 s31, s38, 1
	s_not_b64 s[38:39], s[16:17]
	v_and_b32_e32 v34, 64, v240
	v_xor_b32_e32 v33, 32, v240
	v_add_u32_e32 v34, 64, v34
	v_cmp_lt_i32_e32 vcc, v33, v34
	s_nop 1
	v_cndmask_b32_e32 v33, v240, v33, vcc
	v_lshlrev_b32_e32 v165, 2, v33
	s_mov_b32 s42, s31
	v_subrev_u32_e32 v170, s6, v170
	v_subrev_u32_e32 v172, s10, v172
	s_add_i32 s2, s42, 0
	s_and_b32 s2, s2, 31
	s_mul_i32 s2, s2, 0x44000
	s_add_i32 m0, s5, 0
	s_add_u32 s40, s26, s2
	s_addc_u32 s41, s27, 0
	global_load_lds_dwordx4 v170, s[40:41]
	s_add_i32 m0, s5, 8192
	s_add_u32 s40, s40, 0x80
	s_addc_u32 s41, s41, 0
	global_load_lds_dwordx4 v170, s[40:41]
	s_add_i32 s2, s42, 1
	s_and_b32 s2, s2, 31
	s_mul_i32 s2, s2, 0x44000
	s_add_i32 m0, s5, 16384
	s_add_u32 s40, s26, s2
	s_addc_u32 s41, s27, 0
	global_load_lds_dwordx4 v170, s[40:41]
	s_add_i32 m0, s5, 24576
	s_add_u32 s40, s40, 0x80
	s_addc_u32 s41, s41, 0
	global_load_lds_dwordx4 v170, s[40:41]
	s_add_i32 s2, s42, 0
	s_and_b32 s2, s2, 31
	s_lshl_b32 s2, s2, 7
	s_add_i32 m0, s5, 65536
	s_add_u32 s44, s10, s2
	s_addc_u32 s45, s11, 0
	global_load_lds_dwordx4 v172, s[44:45]
	s_add_i32 m0, s5, 73728
	s_add_u32 s44, s44, 0x204000
	s_addc_u32 s45, s45, 0
	global_load_lds_dwordx4 v172, s[44:45]
	s_add_i32 s2, s42, 2
	s_and_b32 s2, s2, 31
	s_mul_i32 s2, s2, 0x44000
	s_add_i32 m0, s5, 32768
	s_add_u32 s40, s26, s2
	s_addc_u32 s41, s27, 0
	global_load_lds_dwordx4 v170, s[40:41]
	s_add_i32 m0, s5, 40960
	s_add_u32 s40, s40, 0x80
	s_addc_u32 s41, s41, 0
	global_load_lds_dwordx4 v170, s[40:41]
	s_add_i32 s2, s42, 1
	s_and_b32 s2, s2, 31
	s_lshl_b32 s2, s2, 7
	s_add_i32 m0, s5, 81920
	s_add_u32 s44, s10, s2
	s_addc_u32 s45, s11, 0
	global_load_lds_dwordx4 v172, s[44:45]
	s_add_i32 m0, s5, 90112
	s_add_u32 s44, s44, 0x204000
	s_addc_u32 s45, s45, 0
	global_load_lds_dwordx4 v172, s[44:45]
	v_mov_b32_e32 v0, 0
	v_mov_b32_e32 v1, 0
	v_mov_b32_e32 v2, 0
	v_mov_b32_e32 v3, 0
	v_mov_b32_e32 v4, 0
	v_mov_b32_e32 v5, 0
	v_mov_b32_e32 v6, 0
	v_mov_b32_e32 v7, 0
	v_mov_b32_e32 v8, 0
	v_mov_b32_e32 v9, 0
	v_mov_b32_e32 v10, 0
	v_mov_b32_e32 v11, 0
	v_mov_b32_e32 v12, 0
	v_mov_b32_e32 v13, 0
	v_mov_b32_e32 v14, 0
	v_mov_b32_e32 v15, 0
	v_mov_b32_e32 v16, 0
	v_mov_b32_e32 v17, 0
	v_mov_b32_e32 v18, 0
	v_mov_b32_e32 v19, 0
	v_mov_b32_e32 v20, 0
	v_mov_b32_e32 v21, 0
	v_mov_b32_e32 v22, 0
	v_mov_b32_e32 v23, 0
	v_mov_b32_e32 v24, 0
	v_mov_b32_e32 v25, 0
	v_mov_b32_e32 v26, 0
	v_mov_b32_e32 v27, 0
	v_mov_b32_e32 v28, 0
	v_mov_b32_e32 v29, 0
	v_mov_b32_e32 v30, 0
	v_mov_b32_e32 v31, 0
	v_mov_b32_e32 v32, 0
	v_mov_b32_e32 v33, 0
	v_mov_b32_e32 v34, 0
	v_mov_b32_e32 v35, 0
	v_mov_b32_e32 v36, 0
	v_mov_b32_e32 v37, 0
	v_mov_b32_e32 v38, 0
	v_mov_b32_e32 v39, 0
	v_mov_b32_e32 v40, 0
	v_mov_b32_e32 v41, 0
	v_mov_b32_e32 v42, 0
	v_mov_b32_e32 v43, 0
	v_mov_b32_e32 v44, 0
	v_mov_b32_e32 v45, 0
	v_mov_b32_e32 v46, 0
	v_mov_b32_e32 v47, 0
	v_mov_b32_e32 v48, 0
	v_mov_b32_e32 v49, 0
	v_mov_b32_e32 v50, 0
	v_mov_b32_e32 v51, 0
	v_mov_b32_e32 v52, 0
	v_mov_b32_e32 v53, 0
	v_mov_b32_e32 v54, 0
	v_mov_b32_e32 v55, 0
	v_mov_b32_e32 v56, 0
	v_mov_b32_e32 v57, 0
	v_mov_b32_e32 v58, 0
	v_mov_b32_e32 v59, 0
	v_mov_b32_e32 v60, 0
	v_mov_b32_e32 v61, 0
	v_mov_b32_e32 v62, 0
	v_mov_b32_e32 v63, 0
	v_mov_b32_e32 v167, 0
	v_mov_b32_e32 v175, 0
	v_mov_b32_e32 v174, 1.0
	s_waitcnt vmcnt(8)
	s_barrier
	ds_read_b128 v[96:99], v182 offset:0
	ds_read_b128 v[100:103], v182 offset:4096
	ds_read_b128 v[104:107], v183 offset:0
	ds_read_b128 v[108:111], v183 offset:4096
	ds_read_b128 v[112:115], v184 offset:0
	ds_read_b128 v[116:119], v184 offset:4096
	ds_read_b128 v[120:123], v185 offset:0
	ds_read_b128 v[124:127], v185 offset:4096
	s_waitcnt lgkmcnt(0)
	v_mfma_f32_32x32x16_bf16 v[64:79], v[96:99], v[128:131], 0
	v_mfma_f32_32x32x16_bf16 v[80:95], v[100:103], v[128:131], 0
	v_mfma_f32_32x32x16_bf16 v[64:79], v[104:107], v[132:135], v[64:79]
	v_mfma_f32_32x32x16_bf16 v[80:95], v[108:111], v[132:135], v[80:95]
	v_mfma_f32_32x32x16_bf16 v[64:79], v[112:115], v[136:139], v[64:79]
	v_mfma_f32_32x32x16_bf16 v[80:95], v[116:119], v[136:139], v[80:95]
	v_mfma_f32_32x32x16_bf16 v[64:79], v[120:123], v[140:143], v[64:79]
	v_mfma_f32_32x32x16_bf16 v[80:95], v[124:127], v[140:143], v[80:95]
	s_waitcnt vmcnt(4)
	s_barrier
	ds_read_b128 v[208:211], v182 offset:16384
	ds_read_b128 v[212:215], v182 offset:20480
	ds_read_b128 v[216:219], v183 offset:16384
	ds_read_b128 v[220:223], v183 offset:20480
	ds_read_b128 v[224:227], v184 offset:16384
	ds_read_b128 v[228:231], v184 offset:20480
	s_nop 7
	s_waitcnt lgkmcnt(5)
	v_mfma_f32_32x32x16_bf16 v[96:111], v[208:211], v[128:131], 0
	ds_read_b128 v[208:211], v185 offset:16384
	s_add_i32 s2, s42, 3
	v_max3_f32 v254, v64, v65, v66
	s_and_b32 s2, s2, 31
	v_max3_f32 v255, v80, v81, v82
	s_mul_i32 s2, s2, 0x44000
	v_max3_f32 v254, v254, v67, v68
	s_add_i32 m0, s5, 49152
	v_max3_f32 v255, v255, v83, v84
	s_waitcnt lgkmcnt(5)
	v_mfma_f32_32x32x16_bf16 v[112:127], v[212:215], v[128:131], 0
	ds_read_b128 v[212:215], v185 offset:20480
	s_add_u32 s40, s26, s2
	v_max3_f32 v254, v254, v69, v70
	s_addc_u32 s41, s27, 0
	v_max3_f32 v255, v255, v85, v86
	global_load_lds_dwordx4 v170, s[40:41]
	v_max3_f32 v254, v254, v71, v72
	s_add_i32 m0, s5, 57344
	v_max3_f32 v255, v255, v87, v88
	s_waitcnt lgkmcnt(5)
	v_mfma_f32_32x32x16_bf16 v[96:111], v[216:219], v[132:135], v[96:111]
	ds_read_b128 v[216:219], v187 offset:0
	s_add_u32 s40, s40, 0x80
	v_max3_f32 v254, v254, v73, v74
	s_addc_u32 s41, s41, 0
	v_max3_f32 v255, v255, v89, v90
	global_load_lds_dwordx4 v170, s[40:41]
	v_max3_f32 v254, v254, v75, v76
	s_add_i32 s2, s42, 2
	v_max3_f32 v255, v255, v91, v92
	s_waitcnt lgkmcnt(5)
	v_mfma_f32_32x32x16_bf16 v[112:127], v[220:223], v[132:135], v[112:127]
	ds_read_b128 v[220:223], v187 offset:4096
	s_and_b32 s2, s2, 31
	v_max3_f32 v254, v254, v77, v78
	s_lshl_b32 s2, s2, 7
	v_max3_f32 v255, v255, v93, v94
	s_add_i32 m0, s5, 98304
	v_max3_f32 v254, v254, v79, v95
	s_add_u32 s44, s10, s2
	v_max_f32_e32 v254, v254, v255
	s_waitcnt lgkmcnt(5)
	v_mfma_f32_32x32x16_bf16 v[96:111], v[224:227], v[136:139], v[96:111]
	ds_read_b128 v[224:227], v187 offset:8192
	v_mov_b32_e32 v180, 0xc2800000
	v_cmp_lt_f32_e32 vcc, 0x4138aa3b, v254
	v_cmp_gt_f32_e64 s[40:41], v180, v254
	s_addc_u32 s45, s11, 0
	global_load_lds_dwordx4 v172, s[44:45]
	s_add_i32 m0, s5, 106496
	s_add_u32 s44, s44, 0x204000
	s_addc_u32 s45, s45, 0
	s_waitcnt lgkmcnt(5)
	v_mfma_f32_32x32x16_bf16 v[112:127], v[228:231], v[136:139], v[112:127]
	ds_read_b128 v[228:231], v187 offset:12288
	global_load_lds_dwordx4 v172, s[44:45]
	s_or_b64 vcc, vcc, s[40:41]
	s_nop 0
	s_cbranch_vccnz .Lattn_sp_t0
	v_exp_f32_e32 v64, v64
	v_exp_f32_e32 v65, v65
	v_exp_f32_e32 v66, v66
	v_exp_f32_e32 v67, v67
	v_exp_f32_e32 v68, v68
	v_exp_f32_e32 v69, v69
	v_exp_f32_e32 v70, v70
	v_exp_f32_e32 v71, v71
	v_add_f32_e32 v190, v64, v65
	v_add_f32_e32 v191, v66, v67
	v_add_f32_e32 v190, v190, v68
	v_add_f32_e32 v191, v191, v69
	v_add_f32_e32 v190, v190, v70
	v_add_f32_e32 v191, v191, v71
	v_cvt_pk_bf16_f32 v144, v64, v65
	v_cvt_pk_bf16_f32 v145, v66, v67
	v_cvt_pk_bf16_f32 v146, v68, v69
	v_cvt_pk_bf16_f32 v147, v70, v71
	s_waitcnt lgkmcnt(5)
	v_mfma_f32_32x32x16_bf16 v[96:111], v[208:211], v[140:143], v[96:111]
	ds_read_b128 v[208:211], v188 offset:0
	s_waitcnt lgkmcnt(5)
	v_mfma_f32_32x32x16_bf16 v[112:127], v[212:215], v[140:143], v[112:127]
	ds_read_b128 v[212:215], v188 offset:4096
	v_exp_f32_e32 v72, v72
	v_exp_f32_e32 v73, v73
	v_exp_f32_e32 v74, v74
	v_exp_f32_e32 v75, v75
	v_exp_f32_e32 v76, v76
	v_exp_f32_e32 v77, v77
	v_exp_f32_e32 v78, v78
	v_exp_f32_e32 v79, v79
	v_add_f32_e32 v190, v190, v72
	v_add_f32_e32 v191, v191, v73
	v_add_f32_e32 v190, v190, v74
	v_add_f32_e32 v191, v191, v75
	v_add_f32_e32 v190, v190, v76
	v_add_f32_e32 v191, v191, v77
	v_add_f32_e32 v190, v190, v78
	v_add_f32_e32 v191, v191, v79
	v_cvt_pk_bf16_f32 v148, v72, v73
	v_cvt_pk_bf16_f32 v149, v74, v75
	v_cvt_pk_bf16_f32 v150, v76, v77
	v_cvt_pk_bf16_f32 v151, v78, v79
	v_exp_f32_e32 v80, v80
	v_exp_f32_e32 v81, v81
	v_exp_f32_e32 v82, v82
	v_exp_f32_e32 v83, v83
	v_exp_f32_e32 v84, v84
	v_exp_f32_e32 v85, v85
	v_exp_f32_e32 v86, v86
	v_exp_f32_e32 v87, v87
	v_add_f32_e32 v190, v190, v80
	v_add_f32_e32 v191, v191, v81
	v_add_f32_e32 v190, v190, v82
	v_add_f32_e32 v191, v191, v83
	v_add_f32_e32 v190, v190, v84
	v_add_f32_e32 v191, v191, v85
	v_add_f32_e32 v190, v190, v86
	v_add_f32_e32 v191, v191, v87
	v_cvt_pk_bf16_f32 v152, v80, v81
	v_cvt_pk_bf16_f32 v153, v82, v83
	v_cvt_pk_bf16_f32 v154, v84, v85
	v_cvt_pk_bf16_f32 v155, v86, v87
	v_exp_f32_e32 v88, v88
	v_exp_f32_e32 v89, v89
	v_exp_f32_e32 v90, v90
	v_exp_f32_e32 v91, v91
	v_exp_f32_e32 v92, v92
	v_exp_f32_e32 v93, v93
	v_exp_f32_e32 v94, v94
	v_exp_f32_e32 v95, v95
	v_add_f32_e32 v190, v190, v88
	v_add_f32_e32 v191, v191, v89
	v_add_f32_e32 v190, v190, v90
	v_add_f32_e32 v191, v191, v91
	v_add_f32_e32 v190, v190, v92
	v_add_f32_e32 v191, v191, v93
	v_add_f32_e32 v190, v190, v94
	v_add_f32_e32 v191, v191, v95
	v_cvt_pk_bf16_f32 v156, v88, v89
	v_cvt_pk_bf16_f32 v157, v90, v91
	v_cvt_pk_bf16_f32 v158, v92, v93
	v_cvt_pk_bf16_f32 v159, v94, v95
	v_add_f32_e32 v190, v190, v191
	v_add_f32_e32 v167, v167, v190
	s_add_i32 s42, s31, 1
	s_movk_i32 s47, 7
.Lattn_loop_f:
	s_waitcnt vmcnt(4)
	s_barrier
	s_waitcnt lgkmcnt(5)
	v_mfma_f32_32x32x16_bf16 v[48:63], v[216:219], v[144:147], v[48:63]
	ds_read_b128 v[216:219], v188 offset:8192
	s_add_i32 s2, s42, 3
	v_max3_f32 v254, v96, v97, v98
	s_and_b32 s2, s2, 31
	v_max3_f32 v255, v112, v113, v114
	s_mul_i32 s2, s2, 0x44000
	v_max3_f32 v254, v254, v99, v100
	s_add_i32 m0, s5, 0
	v_max3_f32 v255, v255, v115, v116
	s_waitcnt lgkmcnt(5)
	v_mfma_f32_32x32x16_bf16 v[32:47], v[220:223], v[144:147], v[32:47]
	ds_read_b128 v[220:223], v188 offset:12288
	s_add_u32 s40, s26, s2
	v_max3_f32 v254, v254, v101, v102
	s_addc_u32 s41, s27, 0
	v_max3_f32 v255, v255, v117, v118
	global_load_lds_dwordx4 v170, s[40:41]
	v_max3_f32 v254, v254, v103, v104
	s_add_i32 m0, s5, 8192
	v_max3_f32 v255, v255, v119, v120
	s_waitcnt lgkmcnt(5)
	v_mfma_f32_32x32x16_bf16 v[16:31], v[224:227], v[144:147], v[16:31]
	ds_read_b128 v[224:227], v186 offset:0
	s_add_u32 s40, s40, 0x80
	v_max3_f32 v254, v254, v105, v106
	s_addc_u32 s41, s41, 0
	v_max3_f32 v255, v255, v121, v122
	global_load_lds_dwordx4 v170, s[40:41]
	v_max3_f32 v254, v254, v107, v108
	s_add_i32 s2, s42, 2
	v_max3_f32 v255, v255, v123, v124
	s_waitcnt lgkmcnt(5)
	v_mfma_f32_32x32x16_bf16 v[0:15], v[228:231], v[144:147], v[0:15]
	ds_read_b128 v[228:231], v186 offset:4096
	s_and_b32 s2, s2, 31
	v_max3_f32 v254, v254, v109, v110
	s_lshl_b32 s2, s2, 7
	v_max3_f32 v255, v255, v125, v126
	s_add_i32 m0, s5, 114688
	v_max3_f32 v254, v254, v111, v127
	s_add_u32 s44, s10, s2
	v_max_f32_e32 v254, v254, v255
	s_waitcnt lgkmcnt(5)
	v_mfma_f32_32x32x16_bf16 v[48:63], v[208:211], v[148:151], v[48:63]
	ds_read_b128 v[208:211], v186 offset:8192
	v_cmp_lt_f32_e32 vcc, 0x4138aa3b, v254
	s_addc_u32 s45, s11, 0
	global_load_lds_dwordx4 v172, s[44:45]
	s_add_i32 m0, s5, 122880
	s_add_u32 s44, s44, 0x204000
	s_addc_u32 s45, s45, 0
	global_load_lds_dwordx4 v172, s[44:45]
	s_cbranch_vccnz .Lattn_sp_L0
	v_exp_f32_e32 v96, v96
	v_exp_f32_e32 v97, v97
	v_exp_f32_e32 v98, v98
	v_exp_f32_e32 v99, v99
	s_waitcnt lgkmcnt(5)
	v_mfma_f32_32x32x16_bf16 v[32:47], v[212:215], v[148:151], v[32:47]
	ds_read_b128 v[212:215], v186 offset:12288
	v_exp_f32_e32 v100, v100
	v_exp_f32_e32 v101, v101
	v_exp_f32_e32 v102, v102
	v_exp_f32_e32 v103, v103
	s_waitcnt lgkmcnt(5)
	v_mfma_f32_32x32x16_bf16 v[16:31], v[216:219], v[148:151], v[16:31]
	ds_read_b128 v[216:219], v189 offset:0
	v_add_f32_e32 v190, v96, v97
	v_add_f32_e32 v191, v98, v99
	v_add_f32_e32 v190, v190, v100
	v_add_f32_e32 v191, v191, v101
	s_waitcnt lgkmcnt(5)
	v_mfma_f32_32x32x16_bf16 v[0:15], v[220:223], v[148:151], v[0:15]
	ds_read_b128 v[220:223], v189 offset:4096
	v_add_f32_e32 v190, v190, v102
	v_add_f32_e32 v191, v191, v103
	v_cvt_pk_bf16_f32 v144, v96, v97
	v_cvt_pk_bf16_f32 v145, v98, v99
	s_waitcnt lgkmcnt(5)
	v_mfma_f32_32x32x16_bf16 v[48:63], v[224:227], v[152:155], v[48:63]
	ds_read_b128 v[224:227], v189 offset:8192
	v_cvt_pk_bf16_f32 v146, v100, v101
	v_cvt_pk_bf16_f32 v147, v102, v103
	v_exp_f32_e32 v104, v104
	v_exp_f32_e32 v105, v105
	s_waitcnt lgkmcnt(5)
	v_mfma_f32_32x32x16_bf16 v[32:47], v[228:231], v[152:155], v[32:47]
	ds_read_b128 v[228:231], v189 offset:12288
	v_exp_f32_e32 v106, v106
	v_exp_f32_e32 v107, v107
	v_exp_f32_e32 v108, v108
	v_exp_f32_e32 v109, v109
	s_waitcnt lgkmcnt(5)
	v_mfma_f32_32x32x16_bf16 v[16:31], v[208:211], v[152:155], v[16:31]
	ds_read_b128 v[208:211], v182 offset:32768
	v_exp_f32_e32 v110, v110
	v_exp_f32_e32 v111, v111
	v_add_f32_e32 v190, v190, v104
	v_add_f32_e32 v191, v191, v105
	s_waitcnt lgkmcnt(5)
	v_mfma_f32_32x32x16_bf16 v[0:15], v[212:215], v[152:155], v[0:15]
	ds_read_b128 v[212:215], v182 offset:36864
	v_add_f32_e32 v190, v190, v106
	v_add_f32_e32 v191, v191, v107
	v_add_f32_e32 v190, v190, v108
	v_add_f32_e32 v191, v191, v109
	s_waitcnt lgkmcnt(5)
	v_mfma_f32_32x32x16_bf16 v[48:63], v[216:219], v[156:159], v[48:63]
	ds_read_b128 v[216:219], v183 offset:32768
	v_add_f32_e32 v190, v190, v110
	v_add_f32_e32 v191, v191, v111
	v_cvt_pk_bf16_f32 v148, v104, v105
	v_cvt_pk_bf16_f32 v149, v106, v107
	s_waitcnt lgkmcnt(5)
	v_mfma_f32_32x32x16_bf16 v[32:47], v[220:223], v[156:159], v[32:47]
	ds_read_b128 v[220:223], v183 offset:36864
	v_cvt_pk_bf16_f32 v150, v108, v109
	v_cvt_pk_bf16_f32 v151, v110, v111
	v_exp_f32_e32 v112, v112
	v_exp_f32_e32 v113, v113
	s_waitcnt lgkmcnt(5)
	v_mfma_f32_32x32x16_bf16 v[16:31], v[224:227], v[156:159], v[16:31]
	ds_read_b128 v[224:227], v184 offset:32768
	v_exp_f32_e32 v114, v114
	v_exp_f32_e32 v115, v115
	v_exp_f32_e32 v116, v116
	v_exp_f32_e32 v117, v117
	s_waitcnt lgkmcnt(5)
	v_mfma_f32_32x32x16_bf16 v[0:15], v[228:231], v[156:159], v[0:15]
	ds_read_b128 v[228:231], v184 offset:36864
	v_exp_f32_e32 v118, v118
	v_exp_f32_e32 v119, v119
	v_add_f32_e32 v190, v190, v112
	v_add_f32_e32 v191, v191, v113
	s_waitcnt lgkmcnt(5)
	v_mfma_f32_32x32x16_bf16 v[64:79], v[208:211], v[128:131], 0
	ds_read_b128 v[208:211], v185 offset:32768
	v_add_f32_e32 v190, v190, v114
	v_add_f32_e32 v191, v191, v115
	v_add_f32_e32 v190, v190, v116
	v_add_f32_e32 v191, v191, v117
	s_waitcnt lgkmcnt(5)
	v_mfma_f32_32x32x16_bf16 v[80:95], v[212:215], v[128:131], 0
	ds_read_b128 v[212:215], v185 offset:36864
	v_add_f32_e32 v190, v190, v118
	v_add_f32_e32 v191, v191, v119
	v_cvt_pk_bf16_f32 v152, v112, v113
	v_cvt_pk_bf16_f32 v153, v114, v115
	s_waitcnt lgkmcnt(5)
	v_mfma_f32_32x32x16_bf16 v[64:79], v[216:219], v[132:135], v[64:79]
	ds_read_b128 v[216:219], v187 offset:16384
	v_cvt_pk_bf16_f32 v154, v116, v117
	v_cvt_pk_bf16_f32 v155, v118, v119
	v_exp_f32_e32 v120, v120
	v_exp_f32_e32 v121, v121
	s_waitcnt lgkmcnt(5)
	v_mfma_f32_32x32x16_bf16 v[80:95], v[220:223], v[132:135], v[80:95]
	ds_read_b128 v[220:223], v187 offset:20480
	v_exp_f32_e32 v122, v122
	v_exp_f32_e32 v123, v123
	v_exp_f32_e32 v124, v124
	v_exp_f32_e32 v125, v125
	s_waitcnt lgkmcnt(5)
	v_mfma_f32_32x32x16_bf16 v[64:79], v[224:227], v[136:139], v[64:79]
	ds_read_b128 v[224:227], v187 offset:24576
	v_exp_f32_e32 v126, v126
	v_exp_f32_e32 v127, v127
	v_add_f32_e32 v190, v190, v120
	v_add_f32_e32 v191, v191, v121
	s_waitcnt lgkmcnt(5)
	v_mfma_f32_32x32x16_bf16 v[80:95], v[228:231], v[136:139], v[80:95]
	ds_read_b128 v[228:231], v187 offset:28672
	v_add_f32_e32 v190, v190, v122
	v_add_f32_e32 v191, v191, v123
	v_add_f32_e32 v190, v190, v124
	v_add_f32_e32 v191, v191, v125
	s_waitcnt lgkmcnt(5)
	v_mfma_f32_32x32x16_bf16 v[64:79], v[208:211], v[140:143], v[64:79]
	ds_read_b128 v[208:211], v188 offset:16384
	v_add_f32_e32 v190, v190, v126
	v_add_f32_e32 v191, v191, v127
	v_cvt_pk_bf16_f32 v156, v120, v121
	v_cvt_pk_bf16_f32 v157, v122, v123
	s_waitcnt lgkmcnt(5)
	v_mfma_f32_32x32x16_bf16 v[80:95], v[212:215], v[140:143], v[80:95]
	ds_read_b128 v[212:215], v188 offset:20480
	v_cvt_pk_bf16_f32 v158, v124, v125
	v_cvt_pk_bf16_f32 v159, v126, v127
	v_add_f32_e32 v190, v190, v191
	v_add_f32_e32 v167, v167, v190
	s_waitcnt vmcnt(4)
	s_barrier
	s_waitcnt lgkmcnt(5)
	v_mfma_f32_32x32x16_bf16 v[48:63], v[216:219], v[144:147], v[48:63]
	ds_read_b128 v[216:219], v188 offset:24576
	s_add_i32 s2, s42, 4
	v_max3_f32 v254, v64, v65, v66
	s_and_b32 s2, s2, 31
	v_max3_f32 v255, v80, v81, v82
	s_mul_i32 s2, s2, 0x44000
	v_max3_f32 v254, v254, v67, v68
	s_add_i32 m0, s5, 16384
	v_max3_f32 v255, v255, v83, v84
	s_waitcnt lgkmcnt(5)
	v_mfma_f32_32x32x16_bf16 v[32:47], v[220:223], v[144:147], v[32:47]
	ds_read_b128 v[220:223], v188 offset:28672
	s_add_u32 s40, s26, s2
	v_max3_f32 v254, v254, v69, v70
	s_addc_u32 s41, s27, 0
	v_max3_f32 v255, v255, v85, v86
	global_load_lds_dwordx4 v170, s[40:41]
	v_max3_f32 v254, v254, v71, v72
	s_add_i32 m0, s5, 24576
	v_max3_f32 v255, v255, v87, v88
	s_waitcnt lgkmcnt(5)
	v_mfma_f32_32x32x16_bf16 v[16:31], v[224:227], v[144:147], v[16:31]
	ds_read_b128 v[224:227], v186 offset:16384
	s_add_u32 s40, s40, 0x80
	v_max3_f32 v254, v254, v73, v74
	s_addc_u32 s41, s41, 0
	v_max3_f32 v255, v255, v89, v90
	global_load_lds_dwordx4 v170, s[40:41]
	v_max3_f32 v254, v254, v75, v76
	s_add_i32 s2, s42, 3
	v_max3_f32 v255, v255, v91, v92
	s_waitcnt lgkmcnt(5)
	v_mfma_f32_32x32x16_bf16 v[0:15], v[228:231], v[144:147], v[0:15]
	ds_read_b128 v[228:231], v186 offset:20480
	s_and_b32 s2, s2, 31
	v_max3_f32 v254, v254, v77, v78
	s_lshl_b32 s2, s2, 7
	v_max3_f32 v255, v255, v93, v94
	s_add_i32 m0, s5, 65536
	v_max3_f32 v254, v254, v79, v95
	s_add_u32 s44, s10, s2
	v_max_f32_e32 v254, v254, v255
	s_waitcnt lgkmcnt(5)
	v_mfma_f32_32x32x16_bf16 v[48:63], v[208:211], v[148:151], v[48:63]
	ds_read_b128 v[208:211], v186 offset:24576
	v_cmp_lt_f32_e32 vcc, 0x4138aa3b, v254
	s_addc_u32 s45, s11, 0
	global_load_lds_dwordx4 v172, s[44:45]
	s_add_i32 m0, s5, 73728
	s_add_u32 s44, s44, 0x204000
	s_addc_u32 s45, s45, 0
	global_load_lds_dwordx4 v172, s[44:45]
	s_cbranch_vccnz .Lattn_sp_L1
	v_exp_f32_e32 v64, v64
	v_exp_f32_e32 v65, v65
	v_exp_f32_e32 v66, v66
	v_exp_f32_e32 v67, v67
	s_waitcnt lgkmcnt(5)
	v_mfma_f32_32x32x16_bf16 v[32:47], v[212:215], v[148:151], v[32:47]
	ds_read_b128 v[212:215], v186 offset:28672
	v_exp_f32_e32 v68, v68
	v_exp_f32_e32 v69, v69
	v_exp_f32_e32 v70, v70
	v_exp_f32_e32 v71, v71
	s_waitcnt lgkmcnt(5)
	v_mfma_f32_32x32x16_bf16 v[16:31], v[216:219], v[148:151], v[16:31]
	ds_read_b128 v[216:219], v189 offset:16384
	v_add_f32_e32 v190, v64, v65
	v_add_f32_e32 v191, v66, v67
	v_add_f32_e32 v190, v190, v68
	v_add_f32_e32 v191, v191, v69
	s_waitcnt lgkmcnt(5)
	v_mfma_f32_32x32x16_bf16 v[0:15], v[220:223], v[148:151], v[0:15]
	ds_read_b128 v[220:223], v189 offset:20480
	v_add_f32_e32 v190, v190, v70
	v_add_f32_e32 v191, v191, v71
	v_cvt_pk_bf16_f32 v144, v64, v65
	v_cvt_pk_bf16_f32 v145, v66, v67
	s_waitcnt lgkmcnt(5)
	v_mfma_f32_32x32x16_bf16 v[48:63], v[224:227], v[152:155], v[48:63]
	ds_read_b128 v[224:227], v189 offset:24576
	v_cvt_pk_bf16_f32 v146, v68, v69
	v_cvt_pk_bf16_f32 v147, v70, v71
	v_exp_f32_e32 v72, v72
	v_exp_f32_e32 v73, v73
	s_waitcnt lgkmcnt(5)
	v_mfma_f32_32x32x16_bf16 v[32:47], v[228:231], v[152:155], v[32:47]
	ds_read_b128 v[228:231], v189 offset:28672
	v_exp_f32_e32 v74, v74
	v_exp_f32_e32 v75, v75
	v_exp_f32_e32 v76, v76
	v_exp_f32_e32 v77, v77
	s_waitcnt lgkmcnt(5)
	v_mfma_f32_32x32x16_bf16 v[16:31], v[208:211], v[152:155], v[16:31]
	ds_read_b128 v[208:211], v182 offset:49152
	v_exp_f32_e32 v78, v78
	v_exp_f32_e32 v79, v79
	v_add_f32_e32 v190, v190, v72
	v_add_f32_e32 v191, v191, v73
	s_waitcnt lgkmcnt(5)
	v_mfma_f32_32x32x16_bf16 v[0:15], v[212:215], v[152:155], v[0:15]
	ds_read_b128 v[212:215], v182 offset:53248
	v_add_f32_e32 v190, v190, v74
	v_add_f32_e32 v191, v191, v75
	v_add_f32_e32 v190, v190, v76
	v_add_f32_e32 v191, v191, v77
	s_waitcnt lgkmcnt(5)
	v_mfma_f32_32x32x16_bf16 v[48:63], v[216:219], v[156:159], v[48:63]
	ds_read_b128 v[216:219], v183 offset:49152
	v_add_f32_e32 v190, v190, v78
	v_add_f32_e32 v191, v191, v79
	v_cvt_pk_bf16_f32 v148, v72, v73
	v_cvt_pk_bf16_f32 v149, v74, v75
	s_waitcnt lgkmcnt(5)
	v_mfma_f32_32x32x16_bf16 v[32:47], v[220:223], v[156:159], v[32:47]
	ds_read_b128 v[220:223], v183 offset:53248
	v_cvt_pk_bf16_f32 v150, v76, v77
	v_cvt_pk_bf16_f32 v151, v78, v79
	v_exp_f32_e32 v80, v80
	v_exp_f32_e32 v81, v81
	s_waitcnt lgkmcnt(5)
	v_mfma_f32_32x32x16_bf16 v[16:31], v[224:227], v[156:159], v[16:31]
	ds_read_b128 v[224:227], v184 offset:49152
	v_exp_f32_e32 v82, v82
	v_exp_f32_e32 v83, v83
	v_exp_f32_e32 v84, v84
	v_exp_f32_e32 v85, v85
	s_waitcnt lgkmcnt(5)
	v_mfma_f32_32x32x16_bf16 v[0:15], v[228:231], v[156:159], v[0:15]
	ds_read_b128 v[228:231], v184 offset:53248
	v_exp_f32_e32 v86, v86
	v_exp_f32_e32 v87, v87
	v_add_f32_e32 v190, v190, v80
	v_add_f32_e32 v191, v191, v81
	s_waitcnt lgkmcnt(5)
	v_mfma_f32_32x32x16_bf16 v[96:111], v[208:211], v[128:131], 0
	ds_read_b128 v[208:211], v185 offset:49152
	v_add_f32_e32 v190, v190, v82
	v_add_f32_e32 v191, v191, v83
	v_add_f32_e32 v190, v190, v84
	v_add_f32_e32 v191, v191, v85
	s_waitcnt lgkmcnt(5)
	v_mfma_f32_32x32x16_bf16 v[112:127], v[212:215], v[128:131], 0
	ds_read_b128 v[212:215], v185 offset:53248
	v_add_f32_e32 v190, v190, v86
	v_add_f32_e32 v191, v191, v87
	v_cvt_pk_bf16_f32 v152, v80, v81
	v_cvt_pk_bf16_f32 v153, v82, v83
	s_waitcnt lgkmcnt(5)
	v_mfma_f32_32x32x16_bf16 v[96:111], v[216:219], v[132:135], v[96:111]
	ds_read_b128 v[216:219], v187 offset:32768
	v_cvt_pk_bf16_f32 v154, v84, v85
	v_cvt_pk_bf16_f32 v155, v86, v87
	v_exp_f32_e32 v88, v88
	v_exp_f32_e32 v89, v89
	s_waitcnt lgkmcnt(5)
	v_mfma_f32_32x32x16_bf16 v[112:127], v[220:223], v[132:135], v[112:127]
	ds_read_b128 v[220:223], v187 offset:36864
	v_exp_f32_e32 v90, v90
	v_exp_f32_e32 v91, v91
	v_exp_f32_e32 v92, v92
	v_exp_f32_e32 v93, v93
	s_waitcnt lgkmcnt(5)
	v_mfma_f32_32x32x16_bf16 v[96:111], v[224:227], v[136:139], v[96:111]
	ds_read_b128 v[224:227], v187 offset:40960
	v_exp_f32_e32 v94, v94
	v_exp_f32_e32 v95, v95
	v_add_f32_e32 v190, v190, v88
	v_add_f32_e32 v191, v191, v89
	s_waitcnt lgkmcnt(5)
	v_mfma_f32_32x32x16_bf16 v[112:127], v[228:231], v[136:139], v[112:127]
	ds_read_b128 v[228:231], v187 offset:45056
	v_add_f32_e32 v190, v190, v90
	v_add_f32_e32 v191, v191, v91
	v_add_f32_e32 v190, v190, v92
	v_add_f32_e32 v191, v191, v93
	s_waitcnt lgkmcnt(5)
	v_mfma_f32_32x32x16_bf16 v[96:111], v[208:211], v[140:143], v[96:111]
	ds_read_b128 v[208:211], v188 offset:32768
	v_add_f32_e32 v190, v190, v94
	v_add_f32_e32 v191, v191, v95
	v_cvt_pk_bf16_f32 v156, v88, v89
	v_cvt_pk_bf16_f32 v157, v90, v91
	s_waitcnt lgkmcnt(5)
	v_mfma_f32_32x32x16_bf16 v[112:127], v[212:215], v[140:143], v[112:127]
	ds_read_b128 v[212:215], v188 offset:36864
	v_cvt_pk_bf16_f32 v158, v92, v93
	v_cvt_pk_bf16_f32 v159, v94, v95
	v_add_f32_e32 v190, v190, v191
	v_add_f32_e32 v167, v167, v190
	s_waitcnt vmcnt(4)
	s_barrier
	s_waitcnt lgkmcnt(5)
	v_mfma_f32_32x32x16_bf16 v[48:63], v[216:219], v[144:147], v[48:63]
	ds_read_b128 v[216:219], v188 offset:40960
	s_add_i32 s2, s42, 5
	v_max3_f32 v254, v96, v97, v98
	s_and_b32 s2, s2, 31
	v_max3_f32 v255, v112, v113, v114
	s_mul_i32 s2, s2, 0x44000
	v_max3_f32 v254, v254, v99, v100
	s_add_i32 m0, s5, 32768
	v_max3_f32 v255, v255, v115, v116
	s_waitcnt lgkmcnt(5)
	v_mfma_f32_32x32x16_bf16 v[32:47], v[220:223], v[144:147], v[32:47]
	ds_read_b128 v[220:223], v188 offset:45056
	s_add_u32 s40, s26, s2
	v_max3_f32 v254, v254, v101, v102
	s_addc_u32 s41, s27, 0
	v_max3_f32 v255, v255, v117, v118
	global_load_lds_dwordx4 v170, s[40:41]
	v_max3_f32 v254, v254, v103, v104
	s_add_i32 m0, s5, 40960
	v_max3_f32 v255, v255, v119, v120
	s_waitcnt lgkmcnt(5)
	v_mfma_f32_32x32x16_bf16 v[16:31], v[224:227], v[144:147], v[16:31]
	ds_read_b128 v[224:227], v186 offset:32768
	s_add_u32 s40, s40, 0x80
	v_max3_f32 v254, v254, v105, v106
	s_addc_u32 s41, s41, 0
	v_max3_f32 v255, v255, v121, v122
	global_load_lds_dwordx4 v170, s[40:41]
	v_max3_f32 v254, v254, v107, v108
	s_add_i32 s2, s42, 4
	v_max3_f32 v255, v255, v123, v124
	s_waitcnt lgkmcnt(5)
	v_mfma_f32_32x32x16_bf16 v[0:15], v[228:231], v[144:147], v[0:15]
	ds_read_b128 v[228:231], v186 offset:36864
	s_and_b32 s2, s2, 31
	v_max3_f32 v254, v254, v109, v110
	s_lshl_b32 s2, s2, 7
	v_max3_f32 v255, v255, v125, v126
	s_add_i32 m0, s5, 81920
	v_max3_f32 v254, v254, v111, v127
	s_add_u32 s44, s10, s2
	v_max_f32_e32 v254, v254, v255
	s_waitcnt lgkmcnt(5)
	v_mfma_f32_32x32x16_bf16 v[48:63], v[208:211], v[148:151], v[48:63]
	ds_read_b128 v[208:211], v186 offset:40960
	v_cmp_lt_f32_e32 vcc, 0x4138aa3b, v254
	s_addc_u32 s45, s11, 0
	global_load_lds_dwordx4 v172, s[44:45]
	s_add_i32 m0, s5, 90112
	s_add_u32 s44, s44, 0x204000
	s_addc_u32 s45, s45, 0
	global_load_lds_dwordx4 v172, s[44:45]
	s_cbranch_vccnz .Lattn_sp_L2
	v_exp_f32_e32 v96, v96
	v_exp_f32_e32 v97, v97
	v_exp_f32_e32 v98, v98
	v_exp_f32_e32 v99, v99
	s_waitcnt lgkmcnt(5)
	v_mfma_f32_32x32x16_bf16 v[32:47], v[212:215], v[148:151], v[32:47]
	ds_read_b128 v[212:215], v186 offset:45056
	v_exp_f32_e32 v100, v100
	v_exp_f32_e32 v101, v101
	v_exp_f32_e32 v102, v102
	v_exp_f32_e32 v103, v103
	s_waitcnt lgkmcnt(5)
	v_mfma_f32_32x32x16_bf16 v[16:31], v[216:219], v[148:151], v[16:31]
	ds_read_b128 v[216:219], v189 offset:32768
	v_add_f32_e32 v190, v96, v97
	v_add_f32_e32 v191, v98, v99
	v_add_f32_e32 v190, v190, v100
	v_add_f32_e32 v191, v191, v101
	s_waitcnt lgkmcnt(5)
	v_mfma_f32_32x32x16_bf16 v[0:15], v[220:223], v[148:151], v[0:15]
	ds_read_b128 v[220:223], v189 offset:36864
	v_add_f32_e32 v190, v190, v102
	v_add_f32_e32 v191, v191, v103
	v_cvt_pk_bf16_f32 v144, v96, v97
	v_cvt_pk_bf16_f32 v145, v98, v99
	s_waitcnt lgkmcnt(5)
	v_mfma_f32_32x32x16_bf16 v[48:63], v[224:227], v[152:155], v[48:63]
	ds_read_b128 v[224:227], v189 offset:40960
	v_cvt_pk_bf16_f32 v146, v100, v101
	v_cvt_pk_bf16_f32 v147, v102, v103
	v_exp_f32_e32 v104, v104
	v_exp_f32_e32 v105, v105
	s_waitcnt lgkmcnt(5)
	v_mfma_f32_32x32x16_bf16 v[32:47], v[228:231], v[152:155], v[32:47]
	ds_read_b128 v[228:231], v189 offset:45056
	v_exp_f32_e32 v106, v106
	v_exp_f32_e32 v107, v107
	v_exp_f32_e32 v108, v108
	v_exp_f32_e32 v109, v109
	s_waitcnt lgkmcnt(5)
	v_mfma_f32_32x32x16_bf16 v[16:31], v[208:211], v[152:155], v[16:31]
	ds_read_b128 v[208:211], v182 offset:0
	v_exp_f32_e32 v110, v110
	v_exp_f32_e32 v111, v111
	v_add_f32_e32 v190, v190, v104
	v_add_f32_e32 v191, v191, v105
	s_waitcnt lgkmcnt(5)
	v_mfma_f32_32x32x16_bf16 v[0:15], v[212:215], v[152:155], v[0:15]
	ds_read_b128 v[212:215], v182 offset:4096
	v_add_f32_e32 v190, v190, v106
	v_add_f32_e32 v191, v191, v107
	v_add_f32_e32 v190, v190, v108
	v_add_f32_e32 v191, v191, v109
	s_waitcnt lgkmcnt(5)
	v_mfma_f32_32x32x16_bf16 v[48:63], v[216:219], v[156:159], v[48:63]
	ds_read_b128 v[216:219], v183 offset:0
	v_add_f32_e32 v190, v190, v110
	v_add_f32_e32 v191, v191, v111
	v_cvt_pk_bf16_f32 v148, v104, v105
	v_cvt_pk_bf16_f32 v149, v106, v107
	s_waitcnt lgkmcnt(5)
	v_mfma_f32_32x32x16_bf16 v[32:47], v[220:223], v[156:159], v[32:47]
	ds_read_b128 v[220:223], v183 offset:4096
	v_cvt_pk_bf16_f32 v150, v108, v109
	v_cvt_pk_bf16_f32 v151, v110, v111
	v_exp_f32_e32 v112, v112
	v_exp_f32_e32 v113, v113
	s_waitcnt lgkmcnt(5)
	v_mfma_f32_32x32x16_bf16 v[16:31], v[224:227], v[156:159], v[16:31]
	ds_read_b128 v[224:227], v184 offset:0
	v_exp_f32_e32 v114, v114
	v_exp_f32_e32 v115, v115
	v_exp_f32_e32 v116, v116
	v_exp_f32_e32 v117, v117
	s_waitcnt lgkmcnt(5)
	v_mfma_f32_32x32x16_bf16 v[0:15], v[228:231], v[156:159], v[0:15]
	ds_read_b128 v[228:231], v184 offset:4096
	v_exp_f32_e32 v118, v118
	v_exp_f32_e32 v119, v119
	v_add_f32_e32 v190, v190, v112
	v_add_f32_e32 v191, v191, v113
	s_waitcnt lgkmcnt(5)
	v_mfma_f32_32x32x16_bf16 v[64:79], v[208:211], v[128:131], 0
	ds_read_b128 v[208:211], v185 offset:0
	v_add_f32_e32 v190, v190, v114
	v_add_f32_e32 v191, v191, v115
	v_add_f32_e32 v190, v190, v116
	v_add_f32_e32 v191, v191, v117
	s_waitcnt lgkmcnt(5)
	v_mfma_f32_32x32x16_bf16 v[80:95], v[212:215], v[128:131], 0
	ds_read_b128 v[212:215], v185 offset:4096
	v_add_f32_e32 v190, v190, v118
	v_add_f32_e32 v191, v191, v119
	v_cvt_pk_bf16_f32 v152, v112, v113
	v_cvt_pk_bf16_f32 v153, v114, v115
	s_waitcnt lgkmcnt(5)
	v_mfma_f32_32x32x16_bf16 v[64:79], v[216:219], v[132:135], v[64:79]
	ds_read_b128 v[216:219], v187 offset:49152
	v_cvt_pk_bf16_f32 v154, v116, v117
	v_cvt_pk_bf16_f32 v155, v118, v119
	v_exp_f32_e32 v120, v120
	v_exp_f32_e32 v121, v121
	s_waitcnt lgkmcnt(5)
	v_mfma_f32_32x32x16_bf16 v[80:95], v[220:223], v[132:135], v[80:95]
	ds_read_b128 v[220:223], v187 offset:53248
	v_exp_f32_e32 v122, v122
	v_exp_f32_e32 v123, v123
	v_exp_f32_e32 v124, v124
	v_exp_f32_e32 v125, v125
	s_waitcnt lgkmcnt(5)
	v_mfma_f32_32x32x16_bf16 v[64:79], v[224:227], v[136:139], v[64:79]
	ds_read_b128 v[224:227], v187 offset:57344
	v_exp_f32_e32 v126, v126
	v_exp_f32_e32 v127, v127
	v_add_f32_e32 v190, v190, v120
	v_add_f32_e32 v191, v191, v121
	s_waitcnt lgkmcnt(5)
	v_mfma_f32_32x32x16_bf16 v[80:95], v[228:231], v[136:139], v[80:95]
	ds_read_b128 v[228:231], v187 offset:61440
	v_add_f32_e32 v190, v190, v122
	v_add_f32_e32 v191, v191, v123
	v_add_f32_e32 v190, v190, v124
	v_add_f32_e32 v191, v191, v125
	s_waitcnt lgkmcnt(5)
	v_mfma_f32_32x32x16_bf16 v[64:79], v[208:211], v[140:143], v[64:79]
	ds_read_b128 v[208:211], v188 offset:49152
	v_add_f32_e32 v190, v190, v126
	v_add_f32_e32 v191, v191, v127
	v_cvt_pk_bf16_f32 v156, v120, v121
	v_cvt_pk_bf16_f32 v157, v122, v123
	s_waitcnt lgkmcnt(5)
	v_mfma_f32_32x32x16_bf16 v[80:95], v[212:215], v[140:143], v[80:95]
	ds_read_b128 v[212:215], v188 offset:53248
	v_cvt_pk_bf16_f32 v158, v124, v125
	v_cvt_pk_bf16_f32 v159, v126, v127
	v_add_f32_e32 v190, v190, v191
	v_add_f32_e32 v167, v167, v190
	s_waitcnt vmcnt(4)
	s_barrier
	s_waitcnt lgkmcnt(5)
	v_mfma_f32_32x32x16_bf16 v[48:63], v[216:219], v[144:147], v[48:63]
	ds_read_b128 v[216:219], v188 offset:57344
	s_add_i32 s2, s42, 6
	v_max3_f32 v254, v64, v65, v66
	s_and_b32 s2, s2, 31
	v_max3_f32 v255, v80, v81, v82
	s_mul_i32 s2, s2, 0x44000
	v_max3_f32 v254, v254, v67, v68
	s_add_i32 m0, s5, 49152
	v_max3_f32 v255, v255, v83, v84
	s_waitcnt lgkmcnt(5)
	v_mfma_f32_32x32x16_bf16 v[32:47], v[220:223], v[144:147], v[32:47]
	ds_read_b128 v[220:223], v188 offset:61440
	s_add_u32 s40, s26, s2
	v_max3_f32 v254, v254, v69, v70
	s_addc_u32 s41, s27, 0
	v_max3_f32 v255, v255, v85, v86
	global_load_lds_dwordx4 v170, s[40:41]
	v_max3_f32 v254, v254, v71, v72
	s_add_i32 m0, s5, 57344
	v_max3_f32 v255, v255, v87, v88
	s_waitcnt lgkmcnt(5)
	v_mfma_f32_32x32x16_bf16 v[16:31], v[224:227], v[144:147], v[16:31]
	ds_read_b128 v[224:227], v186 offset:49152
	s_add_u32 s40, s40, 0x80
	v_max3_f32 v254, v254, v73, v74
	s_addc_u32 s41, s41, 0
	v_max3_f32 v255, v255, v89, v90
	global_load_lds_dwordx4 v170, s[40:41]
	v_max3_f32 v254, v254, v75, v76
	s_add_i32 s2, s42, 5
	v_max3_f32 v255, v255, v91, v92
	s_waitcnt lgkmcnt(5)
	v_mfma_f32_32x32x16_bf16 v[0:15], v[228:231], v[144:147], v[0:15]
	ds_read_b128 v[228:231], v186 offset:53248
	s_and_b32 s2, s2, 31
	v_max3_f32 v254, v254, v77, v78
	s_lshl_b32 s2, s2, 7
	v_max3_f32 v255, v255, v93, v94
	s_add_i32 m0, s5, 98304
	v_max3_f32 v254, v254, v79, v95
	s_add_u32 s44, s10, s2
	v_max_f32_e32 v254, v254, v255
	s_waitcnt lgkmcnt(5)
	v_mfma_f32_32x32x16_bf16 v[48:63], v[208:211], v[148:151], v[48:63]
	ds_read_b128 v[208:211], v186 offset:57344
	v_cmp_lt_f32_e32 vcc, 0x4138aa3b, v254
	s_addc_u32 s45, s11, 0
	global_load_lds_dwordx4 v172, s[44:45]
	s_add_i32 m0, s5, 106496
	s_add_u32 s44, s44, 0x204000
	s_addc_u32 s45, s45, 0
	global_load_lds_dwordx4 v172, s[44:45]
	s_cbranch_vccnz .Lattn_sp_L3
	v_exp_f32_e32 v64, v64
	v_exp_f32_e32 v65, v65
	v_exp_f32_e32 v66, v66
	v_exp_f32_e32 v67, v67
	s_waitcnt lgkmcnt(5)
	v_mfma_f32_32x32x16_bf16 v[32:47], v[212:215], v[148:151], v[32:47]
	ds_read_b128 v[212:215], v186 offset:61440
	v_exp_f32_e32 v68, v68
	v_exp_f32_e32 v69, v69
	v_exp_f32_e32 v70, v70
	v_exp_f32_e32 v71, v71
	s_waitcnt lgkmcnt(5)
	v_mfma_f32_32x32x16_bf16 v[16:31], v[216:219], v[148:151], v[16:31]
	ds_read_b128 v[216:219], v189 offset:49152
	v_add_f32_e32 v190, v64, v65
	v_add_f32_e32 v191, v66, v67
	v_add_f32_e32 v190, v190, v68
	v_add_f32_e32 v191, v191, v69
	s_waitcnt lgkmcnt(5)
	v_mfma_f32_32x32x16_bf16 v[0:15], v[220:223], v[148:151], v[0:15]
	ds_read_b128 v[220:223], v189 offset:53248
	v_add_f32_e32 v190, v190, v70
	v_add_f32_e32 v191, v191, v71
	v_cvt_pk_bf16_f32 v144, v64, v65
	v_cvt_pk_bf16_f32 v145, v66, v67
	s_waitcnt lgkmcnt(5)
	v_mfma_f32_32x32x16_bf16 v[48:63], v[224:227], v[152:155], v[48:63]
	ds_read_b128 v[224:227], v189 offset:57344
	v_cvt_pk_bf16_f32 v146, v68, v69
	v_cvt_pk_bf16_f32 v147, v70, v71
	v_exp_f32_e32 v72, v72
	v_exp_f32_e32 v73, v73
	s_waitcnt lgkmcnt(5)
	v_mfma_f32_32x32x16_bf16 v[32:47], v[228:231], v[152:155], v[32:47]
	ds_read_b128 v[228:231], v189 offset:61440
	v_exp_f32_e32 v74, v74
	v_exp_f32_e32 v75, v75
	v_exp_f32_e32 v76, v76
	v_exp_f32_e32 v77, v77
	s_waitcnt lgkmcnt(5)
	v_mfma_f32_32x32x16_bf16 v[16:31], v[208:211], v[152:155], v[16:31]
	ds_read_b128 v[208:211], v182 offset:16384
	v_exp_f32_e32 v78, v78
	v_exp_f32_e32 v79, v79
	v_add_f32_e32 v190, v190, v72
	v_add_f32_e32 v191, v191, v73
	s_waitcnt lgkmcnt(5)
	v_mfma_f32_32x32x16_bf16 v[0:15], v[212:215], v[152:155], v[0:15]
	ds_read_b128 v[212:215], v182 offset:20480
	v_add_f32_e32 v190, v190, v74
	v_add_f32_e32 v191, v191, v75
	v_add_f32_e32 v190, v190, v76
	v_add_f32_e32 v191, v191, v77
	s_waitcnt lgkmcnt(5)
	v_mfma_f32_32x32x16_bf16 v[48:63], v[216:219], v[156:159], v[48:63]
	ds_read_b128 v[216:219], v183 offset:16384
	v_add_f32_e32 v190, v190, v78
	v_add_f32_e32 v191, v191, v79
	v_cvt_pk_bf16_f32 v148, v72, v73
	v_cvt_pk_bf16_f32 v149, v74, v75
	s_waitcnt lgkmcnt(5)
	v_mfma_f32_32x32x16_bf16 v[32:47], v[220:223], v[156:159], v[32:47]
	ds_read_b128 v[220:223], v183 offset:20480
	v_cvt_pk_bf16_f32 v150, v76, v77
	v_cvt_pk_bf16_f32 v151, v78, v79
	v_exp_f32_e32 v80, v80
	v_exp_f32_e32 v81, v81
	s_waitcnt lgkmcnt(5)
	v_mfma_f32_32x32x16_bf16 v[16:31], v[224:227], v[156:159], v[16:31]
	ds_read_b128 v[224:227], v184 offset:16384
	v_exp_f32_e32 v82, v82
	v_exp_f32_e32 v83, v83
	v_exp_f32_e32 v84, v84
	v_exp_f32_e32 v85, v85
	s_waitcnt lgkmcnt(5)
	v_mfma_f32_32x32x16_bf16 v[0:15], v[228:231], v[156:159], v[0:15]
	ds_read_b128 v[228:231], v184 offset:20480
	v_exp_f32_e32 v86, v86
	v_exp_f32_e32 v87, v87
	v_add_f32_e32 v190, v190, v80
	v_add_f32_e32 v191, v191, v81
	s_waitcnt lgkmcnt(5)
	v_mfma_f32_32x32x16_bf16 v[96:111], v[208:211], v[128:131], 0
	ds_read_b128 v[208:211], v185 offset:16384
	v_add_f32_e32 v190, v190, v82
	v_add_f32_e32 v191, v191, v83
	v_add_f32_e32 v190, v190, v84
	v_add_f32_e32 v191, v191, v85
	s_waitcnt lgkmcnt(5)
	v_mfma_f32_32x32x16_bf16 v[112:127], v[212:215], v[128:131], 0
	ds_read_b128 v[212:215], v185 offset:20480
	v_add_f32_e32 v190, v190, v86
	v_add_f32_e32 v191, v191, v87
	v_cvt_pk_bf16_f32 v152, v80, v81
	v_cvt_pk_bf16_f32 v153, v82, v83
	s_waitcnt lgkmcnt(5)
	v_mfma_f32_32x32x16_bf16 v[96:111], v[216:219], v[132:135], v[96:111]
	ds_read_b128 v[216:219], v187 offset:0
	v_cvt_pk_bf16_f32 v154, v84, v85
	v_cvt_pk_bf16_f32 v155, v86, v87
	v_exp_f32_e32 v88, v88
	v_exp_f32_e32 v89, v89
	s_waitcnt lgkmcnt(5)
	v_mfma_f32_32x32x16_bf16 v[112:127], v[220:223], v[132:135], v[112:127]
	ds_read_b128 v[220:223], v187 offset:4096
	v_exp_f32_e32 v90, v90
	v_exp_f32_e32 v91, v91
	v_exp_f32_e32 v92, v92
	v_exp_f32_e32 v93, v93
	s_waitcnt lgkmcnt(5)
	v_mfma_f32_32x32x16_bf16 v[96:111], v[224:227], v[136:139], v[96:111]
	ds_read_b128 v[224:227], v187 offset:8192
	v_exp_f32_e32 v94, v94
	v_exp_f32_e32 v95, v95
	v_add_f32_e32 v190, v190, v88
	v_add_f32_e32 v191, v191, v89
	s_waitcnt lgkmcnt(5)
	v_mfma_f32_32x32x16_bf16 v[112:127], v[228:231], v[136:139], v[112:127]
	ds_read_b128 v[228:231], v187 offset:12288
	v_add_f32_e32 v190, v190, v90
	v_add_f32_e32 v191, v191, v91
	v_add_f32_e32 v190, v190, v92
	v_add_f32_e32 v191, v191, v93
	s_waitcnt lgkmcnt(5)
	v_mfma_f32_32x32x16_bf16 v[96:111], v[208:211], v[140:143], v[96:111]
	ds_read_b128 v[208:211], v188 offset:0
	v_add_f32_e32 v190, v190, v94
	v_add_f32_e32 v191, v191, v95
	v_cvt_pk_bf16_f32 v156, v88, v89
	v_cvt_pk_bf16_f32 v157, v90, v91
	s_waitcnt lgkmcnt(5)
	v_mfma_f32_32x32x16_bf16 v[112:127], v[212:215], v[140:143], v[112:127]
	ds_read_b128 v[212:215], v188 offset:4096
	v_cvt_pk_bf16_f32 v158, v92, v93
	v_cvt_pk_bf16_f32 v159, v94, v95
	v_add_f32_e32 v190, v190, v191
	v_add_f32_e32 v167, v167, v190
	s_add_i32 s42, s42, 4
	s_add_i32 s47, s47, -1
	s_cmp_lg_u32 s47, 0
	s_cbranch_scc1 .Lattn_loop_f
	s_waitcnt vmcnt(4)
	s_barrier
	s_waitcnt lgkmcnt(5)
	v_mfma_f32_32x32x16_bf16 v[48:63], v[216:219], v[144:147], v[48:63]
	ds_read_b128 v[216:219], v188 offset:8192
	s_nop 3
	s_add_i32 s2, s42, 2
	v_max3_f32 v254, v96, v97, v98
	s_and_b32 s2, s2, 31
	v_max3_f32 v255, v112, v113, v114
	s_lshl_b32 s2, s2, 7
	v_max3_f32 v254, v254, v99, v100
	s_add_i32 m0, s5, 114688
	s_waitcnt lgkmcnt(5)
	v_mfma_f32_32x32x16_bf16 v[32:47], v[220:223], v[144:147], v[32:47]
	ds_read_b128 v[220:223], v188 offset:12288
	v_max3_f32 v255, v255, v115, v116
	s_add_u32 s44, s10, s2
	v_max3_f32 v254, v254, v101, v102
	v_max3_f32 v255, v255, v117, v118
	v_max3_f32 v254, v254, v103, v104
	v_max3_f32 v255, v255, v119, v120
	v_max3_f32 v254, v254, v105, v106
	v_max3_f32 v255, v255, v121, v122
	s_waitcnt lgkmcnt(5)
	v_mfma_f32_32x32x16_bf16 v[16:31], v[224:227], v[144:147], v[16:31]
	ds_read_b128 v[224:227], v186 offset:0
	v_max3_f32 v254, v254, v107, v108
	v_max3_f32 v255, v255, v123, v124
	v_max3_f32 v254, v254, v109, v110
	v_max3_f32 v255, v255, v125, v126
	v_max3_f32 v254, v254, v111, v127
	v_max_f32_e32 v254, v254, v255
	v_cmp_lt_f32_e32 vcc, 0x4138aa3b, v254
	s_addc_u32 s45, s11, 0
	s_waitcnt lgkmcnt(5)
	v_mfma_f32_32x32x16_bf16 v[0:15], v[228:231], v[144:147], v[0:15]
	ds_read_b128 v[228:231], v186 offset:4096
	global_load_lds_dwordx4 v172, s[44:45]
	s_add_i32 m0, s5, 122880
	s_add_u32 s44, s44, 0x204000
	s_addc_u32 s45, s45, 0
	global_load_lds_dwordx4 v172, s[44:45]
	s_cbranch_vccnz .Lattn_sp_T29
	v_exp_f32_e32 v96, v96
	v_exp_f32_e32 v97, v97
	v_exp_f32_e32 v98, v98
	v_exp_f32_e32 v99, v99
	s_waitcnt lgkmcnt(5)
	v_mfma_f32_32x32x16_bf16 v[48:63], v[208:211], v[148:151], v[48:63]
	ds_read_b128 v[208:211], v186 offset:8192
	v_exp_f32_e32 v100, v100
	v_exp_f32_e32 v101, v101
	v_exp_f32_e32 v102, v102
	v_exp_f32_e32 v103, v103
	s_waitcnt lgkmcnt(5)
	v_mfma_f32_32x32x16_bf16 v[32:47], v[212:215], v[148:151], v[32:47]
	ds_read_b128 v[212:215], v186 offset:12288
	v_add_f32_e32 v190, v96, v97
	v_add_f32_e32 v191, v98, v99
	v_add_f32_e32 v190, v190, v100
	v_add_f32_e32 v191, v191, v101
	s_waitcnt lgkmcnt(5)
	v_mfma_f32_32x32x16_bf16 v[16:31], v[216:219], v[148:151], v[16:31]
	ds_read_b128 v[216:219], v189 offset:0
	v_add_f32_e32 v190, v190, v102
	v_add_f32_e32 v191, v191, v103
	v_cvt_pk_bf16_f32 v144, v96, v97
	v_cvt_pk_bf16_f32 v145, v98, v99
	s_waitcnt lgkmcnt(5)
	v_mfma_f32_32x32x16_bf16 v[0:15], v[220:223], v[148:151], v[0:15]
	ds_read_b128 v[220:223], v189 offset:4096
	v_cvt_pk_bf16_f32 v146, v100, v101
	v_cvt_pk_bf16_f32 v147, v102, v103
	v_exp_f32_e32 v104, v104
	v_exp_f32_e32 v105, v105
	s_waitcnt lgkmcnt(5)
	v_mfma_f32_32x32x16_bf16 v[48:63], v[224:227], v[152:155], v[48:63]
	ds_read_b128 v[224:227], v189 offset:8192
	v_exp_f32_e32 v106, v106
	v_exp_f32_e32 v107, v107
	v_exp_f32_e32 v108, v108
	v_exp_f32_e32 v109, v109
	s_waitcnt lgkmcnt(5)
	v_mfma_f32_32x32x16_bf16 v[32:47], v[228:231], v[152:155], v[32:47]
	ds_read_b128 v[228:231], v189 offset:12288
	v_exp_f32_e32 v110, v110
	v_exp_f32_e32 v111, v111
	v_add_f32_e32 v190, v190, v104
	v_add_f32_e32 v191, v191, v105
	s_waitcnt lgkmcnt(5)
	v_mfma_f32_32x32x16_bf16 v[16:31], v[208:211], v[152:155], v[16:31]
	ds_read_b128 v[208:211], v182 offset:32768
	v_add_f32_e32 v190, v190, v106
	v_add_f32_e32 v191, v191, v107
	v_add_f32_e32 v190, v190, v108
	v_add_f32_e32 v191, v191, v109
	s_waitcnt lgkmcnt(5)
	v_mfma_f32_32x32x16_bf16 v[0:15], v[212:215], v[152:155], v[0:15]
	ds_read_b128 v[212:215], v182 offset:36864
	v_add_f32_e32 v190, v190, v110
	v_add_f32_e32 v191, v191, v111
	v_cvt_pk_bf16_f32 v148, v104, v105
	v_cvt_pk_bf16_f32 v149, v106, v107
	s_waitcnt lgkmcnt(5)
	v_mfma_f32_32x32x16_bf16 v[48:63], v[216:219], v[156:159], v[48:63]
	ds_read_b128 v[216:219], v183 offset:32768
	v_cvt_pk_bf16_f32 v150, v108, v109
	v_cvt_pk_bf16_f32 v151, v110, v111
	v_exp_f32_e32 v112, v112
	v_exp_f32_e32 v113, v113
	s_waitcnt lgkmcnt(5)
	v_mfma_f32_32x32x16_bf16 v[32:47], v[220:223], v[156:159], v[32:47]
	ds_read_b128 v[220:223], v183 offset:36864
	v_exp_f32_e32 v114, v114
	v_exp_f32_e32 v115, v115
	v_exp_f32_e32 v116, v116
	v_exp_f32_e32 v117, v117
	s_waitcnt lgkmcnt(5)
	v_mfma_f32_32x32x16_bf16 v[16:31], v[224:227], v[156:159], v[16:31]
	ds_read_b128 v[224:227], v184 offset:32768
	v_exp_f32_e32 v118, v118
	v_exp_f32_e32 v119, v119
	v_add_f32_e32 v190, v190, v112
	v_add_f32_e32 v191, v191, v113
	s_waitcnt lgkmcnt(5)
	v_mfma_f32_32x32x16_bf16 v[0:15], v[228:231], v[156:159], v[0:15]
	ds_read_b128 v[228:231], v184 offset:36864
	v_add_f32_e32 v190, v190, v114
	v_add_f32_e32 v191, v191, v115
	v_add_f32_e32 v190, v190, v116
	v_add_f32_e32 v191, v191, v117
	s_waitcnt lgkmcnt(5)
	v_mfma_f32_32x32x16_bf16 v[64:79], v[208:211], v[128:131], 0
	ds_read_b128 v[208:211], v185 offset:32768
	v_add_f32_e32 v190, v190, v118
	v_add_f32_e32 v191, v191, v119
	v_cvt_pk_bf16_f32 v152, v112, v113
	v_cvt_pk_bf16_f32 v153, v114, v115
	s_waitcnt lgkmcnt(5)
	v_mfma_f32_32x32x16_bf16 v[80:95], v[212:215], v[128:131], 0
	ds_read_b128 v[212:215], v185 offset:36864
	v_cvt_pk_bf16_f32 v154, v116, v117
	v_cvt_pk_bf16_f32 v155, v118, v119
	v_exp_f32_e32 v120, v120
	v_exp_f32_e32 v121, v121
	s_waitcnt lgkmcnt(5)
	v_mfma_f32_32x32x16_bf16 v[64:79], v[216:219], v[132:135], v[64:79]
	ds_read_b128 v[216:219], v187 offset:16384
	v_exp_f32_e32 v122, v122
	v_exp_f32_e32 v123, v123
	v_exp_f32_e32 v124, v124
	v_exp_f32_e32 v125, v125
	s_waitcnt lgkmcnt(5)
	v_mfma_f32_32x32x16_bf16 v[80:95], v[220:223], v[132:135], v[80:95]
	ds_read_b128 v[220:223], v187 offset:20480
	v_exp_f32_e32 v126, v126
	v_exp_f32_e32 v127, v127
	v_add_f32_e32 v190, v190, v120
	v_add_f32_e32 v191, v191, v121
	s_waitcnt lgkmcnt(5)
	v_mfma_f32_32x32x16_bf16 v[64:79], v[224:227], v[136:139], v[64:79]
	ds_read_b128 v[224:227], v187 offset:24576
	v_add_f32_e32 v190, v190, v122
	v_add_f32_e32 v191, v191, v123
	v_add_f32_e32 v190, v190, v124
	s_waitcnt lgkmcnt(5)
	v_mfma_f32_32x32x16_bf16 v[80:95], v[228:231], v[136:139], v[80:95]
	ds_read_b128 v[228:231], v187 offset:28672
	v_add_f32_e32 v191, v191, v125
	v_add_f32_e32 v190, v190, v126
	v_add_f32_e32 v191, v191, v127
	s_waitcnt lgkmcnt(5)
	v_mfma_f32_32x32x16_bf16 v[64:79], v[208:211], v[140:143], v[64:79]
	ds_read_b128 v[208:211], v188 offset:16384
	v_cvt_pk_bf16_f32 v156, v120, v121
	v_cvt_pk_bf16_f32 v157, v122, v123
	v_cvt_pk_bf16_f32 v158, v124, v125
	s_waitcnt lgkmcnt(5)
	v_mfma_f32_32x32x16_bf16 v[80:95], v[212:215], v[140:143], v[80:95]
	ds_read_b128 v[212:215], v188 offset:20480
	v_cvt_pk_bf16_f32 v159, v126, v127
	v_add_f32_e32 v190, v190, v191
	v_add_f32_e32 v167, v167, v190
	s_waitcnt vmcnt(2)
	s_barrier
	s_waitcnt lgkmcnt(5)
	v_mfma_f32_32x32x16_bf16 v[48:63], v[216:219], v[144:147], v[48:63]
	ds_read_b128 v[216:219], v188 offset:24576
	s_nop 3
	v_max3_f32 v254, v64, v65, v66
	v_max3_f32 v255, v80, v81, v82
	v_max3_f32 v254, v254, v67, v68
	v_max3_f32 v255, v255, v83, v84
	v_max3_f32 v254, v254, v69, v70
	v_max3_f32 v255, v255, v85, v86
	v_max3_f32 v254, v254, v71, v72
	s_waitcnt lgkmcnt(5)
	v_mfma_f32_32x32x16_bf16 v[32:47], v[220:223], v[144:147], v[32:47]
	ds_read_b128 v[220:223], v188 offset:28672
	v_max3_f32 v255, v255, v87, v88
	v_max3_f32 v254, v254, v73, v74
	v_max3_f32 v255, v255, v89, v90
	v_max3_f32 v254, v254, v75, v76
	v_max3_f32 v255, v255, v91, v92
	v_max3_f32 v254, v254, v77, v78
	v_max3_f32 v255, v255, v93, v94
	v_max3_f32 v254, v254, v79, v95
	s_waitcnt lgkmcnt(5)
	v_mfma_f32_32x32x16_bf16 v[16:31], v[224:227], v[144:147], v[16:31]
	ds_read_b128 v[224:227], v186 offset:16384
	v_max_f32_e32 v254, v254, v255
	v_cmp_lt_f32_e32 vcc, 0x4138aa3b, v254
	s_nop 4
	s_cbranch_vccnz .Lattn_sp_T30
	s_waitcnt lgkmcnt(5)
	v_mfma_f32_32x32x16_bf16 v[0:15], v[228:231], v[144:147], v[0:15]
	ds_read_b128 v[228:231], v186 offset:20480
	v_exp_f32_e32 v64, v64
	v_exp_f32_e32 v65, v65
	v_exp_f32_e32 v66, v66
	v_exp_f32_e32 v67, v67
	s_waitcnt lgkmcnt(5)
	v_mfma_f32_32x32x16_bf16 v[48:63], v[208:211], v[148:151], v[48:63]
	ds_read_b128 v[208:211], v186 offset:24576
	v_exp_f32_e32 v68, v68
	v_exp_f32_e32 v69, v69
	v_exp_f32_e32 v70, v70
	v_exp_f32_e32 v71, v71
	s_waitcnt lgkmcnt(5)
	v_mfma_f32_32x32x16_bf16 v[32:47], v[212:215], v[148:151], v[32:47]
	ds_read_b128 v[212:215], v186 offset:28672
	v_add_f32_e32 v190, v64, v65
	v_add_f32_e32 v191, v66, v67
	v_add_f32_e32 v190, v190, v68
	v_add_f32_e32 v191, v191, v69
	s_waitcnt lgkmcnt(5)
	v_mfma_f32_32x32x16_bf16 v[16:31], v[216:219], v[148:151], v[16:31]
	ds_read_b128 v[216:219], v189 offset:16384
	v_add_f32_e32 v190, v190, v70
	v_add_f32_e32 v191, v191, v71
	v_cvt_pk_bf16_f32 v144, v64, v65
	v_cvt_pk_bf16_f32 v145, v66, v67
	s_waitcnt lgkmcnt(5)
	v_mfma_f32_32x32x16_bf16 v[0:15], v[220:223], v[148:151], v[0:15]
	ds_read_b128 v[220:223], v189 offset:20480
	v_cvt_pk_bf16_f32 v146, v68, v69
	v_cvt_pk_bf16_f32 v147, v70, v71
	v_exp_f32_e32 v72, v72
	v_exp_f32_e32 v73, v73
	s_waitcnt lgkmcnt(5)
	v_mfma_f32_32x32x16_bf16 v[48:63], v[224:227], v[152:155], v[48:63]
	ds_read_b128 v[224:227], v189 offset:24576
	v_exp_f32_e32 v74, v74
	v_exp_f32_e32 v75, v75
	v_exp_f32_e32 v76, v76
	v_exp_f32_e32 v77, v77
	s_waitcnt lgkmcnt(5)
	v_mfma_f32_32x32x16_bf16 v[32:47], v[228:231], v[152:155], v[32:47]
	ds_read_b128 v[228:231], v189 offset:28672
	v_exp_f32_e32 v78, v78
	v_exp_f32_e32 v79, v79
	v_add_f32_e32 v190, v190, v72
	v_add_f32_e32 v191, v191, v73
	s_waitcnt lgkmcnt(5)
	v_mfma_f32_32x32x16_bf16 v[16:31], v[208:211], v[152:155], v[16:31]
	ds_read_b128 v[208:211], v182 offset:49152
	v_add_f32_e32 v190, v190, v74
	v_add_f32_e32 v191, v191, v75
	v_add_f32_e32 v190, v190, v76
	v_add_f32_e32 v191, v191, v77
	s_waitcnt lgkmcnt(5)
	v_mfma_f32_32x32x16_bf16 v[0:15], v[212:215], v[152:155], v[0:15]
	ds_read_b128 v[212:215], v182 offset:53248
	v_add_f32_e32 v190, v190, v78
	v_add_f32_e32 v191, v191, v79
	v_cvt_pk_bf16_f32 v148, v72, v73
	v_cvt_pk_bf16_f32 v149, v74, v75
	s_waitcnt lgkmcnt(5)
	v_mfma_f32_32x32x16_bf16 v[48:63], v[216:219], v[156:159], v[48:63]
	ds_read_b128 v[216:219], v183 offset:49152
	v_cvt_pk_bf16_f32 v150, v76, v77
	v_cvt_pk_bf16_f32 v151, v78, v79
	v_exp_f32_e32 v80, v80
	v_exp_f32_e32 v81, v81
	s_waitcnt lgkmcnt(5)
	v_mfma_f32_32x32x16_bf16 v[32:47], v[220:223], v[156:159], v[32:47]
	ds_read_b128 v[220:223], v183 offset:53248
	v_exp_f32_e32 v82, v82
	v_exp_f32_e32 v83, v83
	v_exp_f32_e32 v84, v84
	v_exp_f32_e32 v85, v85
	s_waitcnt lgkmcnt(5)
	v_mfma_f32_32x32x16_bf16 v[16:31], v[224:227], v[156:159], v[16:31]
	ds_read_b128 v[224:227], v184 offset:49152
	v_exp_f32_e32 v86, v86
	v_exp_f32_e32 v87, v87
	v_add_f32_e32 v190, v190, v80
	v_add_f32_e32 v191, v191, v81
	s_waitcnt lgkmcnt(5)
	v_mfma_f32_32x32x16_bf16 v[0:15], v[228:231], v[156:159], v[0:15]
	ds_read_b128 v[228:231], v184 offset:53248
	v_add_f32_e32 v190, v190, v82
	v_add_f32_e32 v191, v191, v83
	v_add_f32_e32 v190, v190, v84
	v_add_f32_e32 v191, v191, v85
	s_waitcnt lgkmcnt(5)
	v_mfma_f32_32x32x16_bf16 v[96:111], v[208:211], v[128:131], 0
	ds_read_b128 v[208:211], v185 offset:49152
	v_add_f32_e32 v190, v190, v86
	v_add_f32_e32 v191, v191, v87
	v_cvt_pk_bf16_f32 v152, v80, v81
	v_cvt_pk_bf16_f32 v153, v82, v83
	s_waitcnt lgkmcnt(5)
	v_mfma_f32_32x32x16_bf16 v[112:127], v[212:215], v[128:131], 0
	ds_read_b128 v[212:215], v185 offset:53248
	v_cvt_pk_bf16_f32 v154, v84, v85
	v_cvt_pk_bf16_f32 v155, v86, v87
	v_exp_f32_e32 v88, v88
	v_exp_f32_e32 v89, v89
	s_waitcnt lgkmcnt(5)
	v_mfma_f32_32x32x16_bf16 v[96:111], v[216:219], v[132:135], v[96:111]
	ds_read_b128 v[216:219], v187 offset:32768
	v_exp_f32_e32 v90, v90
	v_exp_f32_e32 v91, v91
	v_exp_f32_e32 v92, v92
	v_exp_f32_e32 v93, v93
	s_waitcnt lgkmcnt(5)
	v_mfma_f32_32x32x16_bf16 v[112:127], v[220:223], v[132:135], v[112:127]
	ds_read_b128 v[220:223], v187 offset:36864
	v_exp_f32_e32 v94, v94
	v_exp_f32_e32 v95, v95
	v_add_f32_e32 v190, v190, v88
	v_add_f32_e32 v191, v191, v89
	s_waitcnt lgkmcnt(5)
	v_mfma_f32_32x32x16_bf16 v[96:111], v[224:227], v[136:139], v[96:111]
	ds_read_b128 v[224:227], v187 offset:40960
	v_add_f32_e32 v190, v190, v90
	v_add_f32_e32 v191, v191, v91
	v_add_f32_e32 v190, v190, v92
	s_waitcnt lgkmcnt(5)
	v_mfma_f32_32x32x16_bf16 v[112:127], v[228:231], v[136:139], v[112:127]
	ds_read_b128 v[228:231], v187 offset:45056
	v_add_f32_e32 v191, v191, v93
	v_add_f32_e32 v190, v190, v94
	v_add_f32_e32 v191, v191, v95
	s_waitcnt lgkmcnt(5)
	v_mfma_f32_32x32x16_bf16 v[96:111], v[208:211], v[140:143], v[96:111]
	ds_read_b128 v[208:211], v188 offset:32768
	v_cvt_pk_bf16_f32 v156, v88, v89
	v_cvt_pk_bf16_f32 v157, v90, v91
	v_cvt_pk_bf16_f32 v158, v92, v93
	s_waitcnt lgkmcnt(5)
	v_mfma_f32_32x32x16_bf16 v[112:127], v[212:215], v[140:143], v[112:127]
	ds_read_b128 v[212:215], v188 offset:36864
	v_cvt_pk_bf16_f32 v159, v94, v95
	v_add_f32_e32 v190, v190, v191
	v_add_f32_e32 v167, v167, v190
	s_waitcnt vmcnt(0)
	s_barrier
	s_waitcnt lgkmcnt(5)
	v_mfma_f32_32x32x16_bf16 v[48:63], v[216:219], v[144:147], v[48:63]
	ds_read_b128 v[216:219], v188 offset:40960
	s_nop 3
	v_max3_f32 v254, v96, v97, v98
	v_max3_f32 v255, v112, v113, v114
	v_max3_f32 v254, v254, v99, v100
	v_max3_f32 v255, v255, v115, v116
	v_max3_f32 v254, v254, v101, v102
	v_max3_f32 v255, v255, v117, v118
	v_max3_f32 v254, v254, v103, v104
	s_waitcnt lgkmcnt(5)
	v_mfma_f32_32x32x16_bf16 v[32:47], v[220:223], v[144:147], v[32:47]
	ds_read_b128 v[220:223], v188 offset:45056
	v_max3_f32 v255, v255, v119, v120
	v_max3_f32 v254, v254, v105, v106
	v_max3_f32 v255, v255, v121, v122
	v_max3_f32 v254, v254, v107, v108
	v_max3_f32 v255, v255, v123, v124
	v_max3_f32 v254, v254, v109, v110
	v_max3_f32 v255, v255, v125, v126
	v_max3_f32 v254, v254, v111, v127
	s_waitcnt lgkmcnt(5)
	v_mfma_f32_32x32x16_bf16 v[16:31], v[224:227], v[144:147], v[16:31]
	ds_read_b128 v[224:227], v186 offset:32768
	v_max_f32_e32 v254, v254, v255
	v_cmp_lt_f32_e32 vcc, 0x4138aa3b, v254
	s_nop 4
	s_cbranch_vccnz .Lattn_sp_T31
	s_waitcnt lgkmcnt(5)
	v_mfma_f32_32x32x16_bf16 v[0:15], v[228:231], v[144:147], v[0:15]
	ds_read_b128 v[228:231], v186 offset:36864
	v_exp_f32_e32 v96, v96
	v_exp_f32_e32 v97, v97
	v_exp_f32_e32 v98, v98
	v_exp_f32_e32 v99, v99
	v_exp_f32_e32 v100, v100
	v_exp_f32_e32 v101, v101
	v_exp_f32_e32 v102, v102
	s_waitcnt lgkmcnt(5)
	v_mfma_f32_32x32x16_bf16 v[48:63], v[208:211], v[148:151], v[48:63]
	ds_read_b128 v[208:211], v186 offset:40960
	v_exp_f32_e32 v103, v103
	v_add_f32_e32 v190, v96, v97
	v_add_f32_e32 v191, v98, v99
	v_add_f32_e32 v190, v190, v100
	v_add_f32_e32 v191, v191, v101
	v_add_f32_e32 v190, v190, v102
	v_add_f32_e32 v191, v191, v103
	s_waitcnt lgkmcnt(5)
	v_mfma_f32_32x32x16_bf16 v[32:47], v[212:215], v[148:151], v[32:47]
	ds_read_b128 v[212:215], v186 offset:45056
	v_cvt_pk_bf16_f32 v144, v96, v97
	v_cvt_pk_bf16_f32 v145, v98, v99
	v_cvt_pk_bf16_f32 v146, v100, v101
	v_cvt_pk_bf16_f32 v147, v102, v103
	s_waitcnt lgkmcnt(5)
	v_mfma_f32_32x32x16_bf16 v[16:31], v[216:219], v[148:151], v[16:31]
	ds_read_b128 v[216:219], v189 offset:32768
	s_waitcnt lgkmcnt(5)
	v_mfma_f32_32x32x16_bf16 v[0:15], v[220:223], v[148:151], v[0:15]
	ds_read_b128 v[220:223], v189 offset:36864
	v_exp_f32_e32 v104, v104
	v_exp_f32_e32 v105, v105
	v_exp_f32_e32 v106, v106
	v_exp_f32_e32 v107, v107
	v_exp_f32_e32 v108, v108
	v_exp_f32_e32 v109, v109
	v_exp_f32_e32 v110, v110
	s_waitcnt lgkmcnt(5)
	v_mfma_f32_32x32x16_bf16 v[48:63], v[224:227], v[152:155], v[48:63]
	ds_read_b128 v[224:227], v189 offset:40960
	v_exp_f32_e32 v111, v111
	v_add_f32_e32 v190, v190, v104
	v_add_f32_e32 v191, v191, v105
	v_add_f32_e32 v190, v190, v106
	v_add_f32_e32 v191, v191, v107
	v_add_f32_e32 v190, v190, v108
	v_add_f32_e32 v191, v191, v109
	s_waitcnt lgkmcnt(5)
	v_mfma_f32_32x32x16_bf16 v[32:47], v[228:231], v[152:155], v[32:47]
	ds_read_b128 v[228:231], v189 offset:45056
	v_add_f32_e32 v190, v190, v110
	v_add_f32_e32 v191, v191, v111
	v_cvt_pk_bf16_f32 v148, v104, v105
	v_cvt_pk_bf16_f32 v149, v106, v107
	v_cvt_pk_bf16_f32 v150, v108, v109
	v_cvt_pk_bf16_f32 v151, v110, v111
	s_waitcnt lgkmcnt(5)
	v_mfma_f32_32x32x16_bf16 v[16:31], v[208:211], v[152:155], v[16:31]
	ds_read_b128 v[208:211], v187 offset:49152
	s_waitcnt lgkmcnt(5)
	v_mfma_f32_32x32x16_bf16 v[0:15], v[212:215], v[152:155], v[0:15]
	ds_read_b128 v[212:215], v187 offset:53248
	v_exp_f32_e32 v112, v112
	v_exp_f32_e32 v113, v113
	v_exp_f32_e32 v114, v114
	v_exp_f32_e32 v115, v115
	v_exp_f32_e32 v116, v116
	v_exp_f32_e32 v117, v117
	v_exp_f32_e32 v118, v118
	v_exp_f32_e32 v119, v119
	v_add_f32_e32 v190, v190, v112
	s_waitcnt lgkmcnt(5)
	v_mfma_f32_32x32x16_bf16 v[48:63], v[216:219], v[156:159], v[48:63]
	ds_read_b128 v[216:219], v187 offset:57344
	v_add_f32_e32 v191, v191, v113
	v_add_f32_e32 v190, v190, v114
	v_add_f32_e32 v191, v191, v115
	v_add_f32_e32 v190, v190, v116
	v_add_f32_e32 v191, v191, v117
	v_add_f32_e32 v190, v190, v118
	v_add_f32_e32 v191, v191, v119
	v_cvt_pk_bf16_f32 v152, v112, v113
	v_cvt_pk_bf16_f32 v153, v114, v115
	s_waitcnt lgkmcnt(5)
	v_mfma_f32_32x32x16_bf16 v[32:47], v[220:223], v[156:159], v[32:47]
	ds_read_b128 v[220:223], v187 offset:61440
	v_cvt_pk_bf16_f32 v154, v116, v117
	v_cvt_pk_bf16_f32 v155, v118, v119
	s_waitcnt lgkmcnt(5)
	v_mfma_f32_32x32x16_bf16 v[16:31], v[224:227], v[156:159], v[16:31]
	ds_read_b128 v[224:227], v188 offset:49152
	s_waitcnt lgkmcnt(5)
	v_mfma_f32_32x32x16_bf16 v[0:15], v[228:231], v[156:159], v[0:15]
	ds_read_b128 v[228:231], v188 offset:53248
	v_exp_f32_e32 v120, v120
	v_exp_f32_e32 v121, v121
	v_exp_f32_e32 v122, v122
	v_exp_f32_e32 v123, v123
	v_exp_f32_e32 v124, v124
	v_exp_f32_e32 v125, v125
	v_exp_f32_e32 v126, v126
	v_exp_f32_e32 v127, v127
	v_add_f32_e32 v190, v190, v120
	v_add_f32_e32 v191, v191, v121
	v_add_f32_e32 v190, v190, v122
	v_add_f32_e32 v191, v191, v123
	v_add_f32_e32 v190, v190, v124
	v_add_f32_e32 v191, v191, v125
	v_add_f32_e32 v190, v190, v126
	v_add_f32_e32 v191, v191, v127
	v_cvt_pk_bf16_f32 v156, v120, v121
	v_cvt_pk_bf16_f32 v157, v122, v123
	v_cvt_pk_bf16_f32 v158, v124, v125
	v_cvt_pk_bf16_f32 v159, v126, v127
	v_add_f32_e32 v190, v190, v191
	v_add_f32_e32 v167, v167, v190
.Lattn_final:
	s_waitcnt lgkmcnt(5)
	v_mfma_f32_32x32x16_bf16 v[48:63], v[208:211], v[144:147], v[48:63]
	ds_read_b128 v[208:211], v188 offset:57344
	s_waitcnt lgkmcnt(5)
	v_mfma_f32_32x32x16_bf16 v[32:47], v[212:215], v[144:147], v[32:47]
	ds_read_b128 v[212:215], v188 offset:61440
	s_waitcnt lgkmcnt(5)
	v_mfma_f32_32x32x16_bf16 v[16:31], v[216:219], v[144:147], v[16:31]
	ds_read_b128 v[216:219], v186 offset:49152
	s_waitcnt lgkmcnt(5)
	v_mfma_f32_32x32x16_bf16 v[0:15], v[220:223], v[144:147], v[0:15]
	ds_read_b128 v[220:223], v186 offset:53248
	s_waitcnt lgkmcnt(5)
	v_mfma_f32_32x32x16_bf16 v[48:63], v[224:227], v[148:151], v[48:63]
	ds_read_b128 v[224:227], v186 offset:57344
	s_waitcnt lgkmcnt(5)
	v_mfma_f32_32x32x16_bf16 v[32:47], v[228:231], v[148:151], v[32:47]
	ds_read_b128 v[228:231], v186 offset:61440
	s_waitcnt lgkmcnt(5)
	v_mfma_f32_32x32x16_bf16 v[16:31], v[208:211], v[148:151], v[16:31]
	ds_read_b128 v[208:211], v189 offset:49152
	s_waitcnt lgkmcnt(5)
	v_mfma_f32_32x32x16_bf16 v[0:15], v[212:215], v[148:151], v[0:15]
	ds_read_b128 v[212:215], v189 offset:53248
	s_waitcnt lgkmcnt(5)
	v_mfma_f32_32x32x16_bf16 v[48:63], v[216:219], v[152:155], v[48:63]
	ds_read_b128 v[216:219], v189 offset:57344
	s_waitcnt lgkmcnt(5)
	v_mfma_f32_32x32x16_bf16 v[32:47], v[220:223], v[152:155], v[32:47]
	ds_read_b128 v[220:223], v189 offset:61440
	s_waitcnt lgkmcnt(5)
	v_mfma_f32_32x32x16_bf16 v[16:31], v[224:227], v[152:155], v[16:31]
	s_waitcnt lgkmcnt(4)
	v_mfma_f32_32x32x16_bf16 v[0:15], v[228:231], v[152:155], v[0:15]
	s_waitcnt lgkmcnt(3)
	v_mfma_f32_32x32x16_bf16 v[48:63], v[208:211], v[156:159], v[48:63]
	s_waitcnt lgkmcnt(2)
	v_mfma_f32_32x32x16_bf16 v[32:47], v[212:215], v[156:159], v[32:47]
	s_waitcnt lgkmcnt(1)
	v_mfma_f32_32x32x16_bf16 v[16:31], v[216:219], v[156:159], v[16:31]
	s_waitcnt lgkmcnt(0)
	v_mfma_f32_32x32x16_bf16 v[0:15], v[220:223], v[156:159], v[0:15]
	s_nop 15
	s_nop 7
	v_mov_b32_e32 v64, v167
	s_branch .Lattn_end
	s_waitcnt lgkmcnt(5)
	v_mfma_f32_32x32x16_bf16 v[96:111], v[208:211], v[128:131], 0
	ds_read_b128 v[208:211], v185 offset:16384
	s_add_i32 s2, s42, 3
	v_max3_f32 v254, v64, v65, v66
	s_and_b32 s2, s2, 31
	v_max3_f32 v255, v80, v81, v82
	s_mul_i32 s2, s2, 0x44000
	v_max3_f32 v254, v254, v67, v68
	s_add_i32 m0, s5, 49152
	v_max3_f32 v255, v255, v83, v84
	s_waitcnt lgkmcnt(5)
	v_mfma_f32_32x32x16_bf16 v[112:127], v[212:215], v[128:131], 0
	ds_read_b128 v[212:215], v185 offset:20480
	s_add_u32 s40, s26, s2
	v_max3_f32 v254, v254, v69, v70
	s_addc_u32 s41, s27, 0
	v_max3_f32 v255, v255, v85, v86
	global_load_lds_dwordx4 v170, s[40:41]
	v_max3_f32 v254, v254, v71, v72
	s_add_i32 m0, s5, 57344
	v_max3_f32 v255, v255, v87, v88
	s_waitcnt lgkmcnt(5)
	v_mfma_f32_32x32x16_bf16 v[96:111], v[216:219], v[132:135], v[96:111]
	ds_read_b128 v[216:219], v187 offset:0
	s_add_u32 s40, s40, 0x80
	v_max3_f32 v254, v254, v73, v74
	s_addc_u32 s41, s41, 0
	v_max3_f32 v255, v255, v89, v90
	global_load_lds_dwordx4 v170, s[40:41]
	v_max3_f32 v254, v254, v75, v76
	s_add_i32 s2, s42, 2
	v_max3_f32 v255, v255, v91, v92
	s_waitcnt lgkmcnt(5)
	v_mfma_f32_32x32x16_bf16 v[112:127], v[220:223], v[132:135], v[112:127]
	ds_read_b128 v[220:223], v187 offset:4096
	s_and_b32 s2, s2, 31
	v_max3_f32 v254, v254, v77, v78
	s_lshl_b32 s2, s2, 7
	v_max3_f32 v255, v255, v93, v94
	s_add_i32 m0, s5, 98304
	v_max3_f32 v254, v254, v79, v95
	s_add_u32 s44, s10, s2
	v_max_f32_e32 v254, v254, v255
	s_waitcnt lgkmcnt(5)
	v_mfma_f32_32x32x16_bf16 v[96:111], v[224:227], v[136:139], v[96:111]
	ds_read_b128 v[224:227], v187 offset:8192
	v_mov_b32_e32 v180, 0xc2800000
	v_cmp_lt_f32_e32 vcc, 0x4138aa3b, v254
	v_cmp_gt_f32_e64 s[40:41], v180, v254
	s_addc_u32 s45, s11, 0
	global_load_lds_dwordx4 v172, s[44:45]
	s_add_i32 m0, s5, 106496
	s_add_u32 s44, s44, 0x204000
	s_addc_u32 s45, s45, 0
	s_waitcnt lgkmcnt(5)
	v_mfma_f32_32x32x16_bf16 v[112:127], v[228:231], v[136:139], v[112:127]
	ds_read_b128 v[228:231], v187 offset:12288
	global_load_lds_dwordx4 v172, s[44:45]
	s_or_b64 vcc, vcc, s[40:41]
	s_nop 0
.Lattn_sp_t0:
	v_mov_b32_e32 v175, v243
	v_mov_b32_e32 v255, v254
	s_nop 1
	v_permlane32_swap_b32_e32 v254, v255
	v_max_f32_e32 v254, v254, v255
	v_add_f32_e32 v180, 0x4138aa3b, v175
	v_cmp_gt_f32_e32 vcc, v254, v180
	s_nop 1
	v_cndmask_b32_e32 v180, v175, v254, vcc
	v_sub_f32_e32 v255, v175, v180
	v_exp_f32_e32 v174, v255
	v_mov_b32_e32 v175, v180
	v_sub_f32_e32 v64, v64, v175
	v_sub_f32_e32 v65, v65, v175
	v_sub_f32_e32 v66, v66, v175
	v_sub_f32_e32 v67, v67, v175
	v_sub_f32_e32 v68, v68, v175
	v_sub_f32_e32 v69, v69, v175
	v_sub_f32_e32 v70, v70, v175
	v_sub_f32_e32 v71, v71, v175
	v_exp_f32_e32 v64, v64
	v_exp_f32_e32 v65, v65
	v_exp_f32_e32 v66, v66
	v_exp_f32_e32 v67, v67
	v_exp_f32_e32 v68, v68
	v_exp_f32_e32 v69, v69
	v_exp_f32_e32 v70, v70
	v_exp_f32_e32 v71, v71
	v_add_f32_e32 v190, v64, v65
	v_add_f32_e32 v191, v66, v67
	v_add_f32_e32 v190, v190, v68
	v_add_f32_e32 v191, v191, v69
	v_add_f32_e32 v190, v190, v70
	v_add_f32_e32 v191, v191, v71
	v_cvt_pk_bf16_f32 v144, v64, v65
	v_cvt_pk_bf16_f32 v145, v66, v67
	v_cvt_pk_bf16_f32 v146, v68, v69
	v_cvt_pk_bf16_f32 v147, v70, v71
	s_waitcnt lgkmcnt(5)
	v_mfma_f32_32x32x16_bf16 v[96:111], v[208:211], v[140:143], v[96:111]
	ds_read_b128 v[208:211], v188 offset:0
	s_waitcnt lgkmcnt(5)
	v_mfma_f32_32x32x16_bf16 v[112:127], v[212:215], v[140:143], v[112:127]
	ds_read_b128 v[212:215], v188 offset:4096
	v_sub_f32_e32 v72, v72, v175
	v_sub_f32_e32 v73, v73, v175
	v_sub_f32_e32 v74, v74, v175
	v_sub_f32_e32 v75, v75, v175
	v_sub_f32_e32 v76, v76, v175
	v_sub_f32_e32 v77, v77, v175
	v_sub_f32_e32 v78, v78, v175
	v_sub_f32_e32 v79, v79, v175
	v_exp_f32_e32 v72, v72
	v_exp_f32_e32 v73, v73
	v_exp_f32_e32 v74, v74
	v_exp_f32_e32 v75, v75
	v_exp_f32_e32 v76, v76
	v_exp_f32_e32 v77, v77
	v_exp_f32_e32 v78, v78
	v_exp_f32_e32 v79, v79
	v_add_f32_e32 v190, v190, v72
	v_add_f32_e32 v191, v191, v73
	v_add_f32_e32 v190, v190, v74
	v_add_f32_e32 v191, v191, v75
	v_add_f32_e32 v190, v190, v76
	v_add_f32_e32 v191, v191, v77
	v_add_f32_e32 v190, v190, v78
	v_add_f32_e32 v191, v191, v79
	v_cvt_pk_bf16_f32 v148, v72, v73
	v_cvt_pk_bf16_f32 v149, v74, v75
	v_cvt_pk_bf16_f32 v150, v76, v77
	v_cvt_pk_bf16_f32 v151, v78, v79
	v_sub_f32_e32 v80, v80, v175
	v_sub_f32_e32 v81, v81, v175
	v_sub_f32_e32 v82, v82, v175
	v_sub_f32_e32 v83, v83, v175
	v_sub_f32_e32 v84, v84, v175
	v_sub_f32_e32 v85, v85, v175
	v_sub_f32_e32 v86, v86, v175
	v_sub_f32_e32 v87, v87, v175
	v_exp_f32_e32 v80, v80
	v_exp_f32_e32 v81, v81
	v_exp_f32_e32 v82, v82
	v_exp_f32_e32 v83, v83
	v_exp_f32_e32 v84, v84
	v_exp_f32_e32 v85, v85
	v_exp_f32_e32 v86, v86
	v_exp_f32_e32 v87, v87
	v_add_f32_e32 v190, v190, v80
	v_add_f32_e32 v191, v191, v81
	v_add_f32_e32 v190, v190, v82
	v_add_f32_e32 v191, v191, v83
	v_add_f32_e32 v190, v190, v84
	v_add_f32_e32 v191, v191, v85
	v_add_f32_e32 v190, v190, v86
	v_add_f32_e32 v191, v191, v87
	v_cvt_pk_bf16_f32 v152, v80, v81
	v_cvt_pk_bf16_f32 v153, v82, v83
	v_cvt_pk_bf16_f32 v154, v84, v85
	v_cvt_pk_bf16_f32 v155, v86, v87
	v_sub_f32_e32 v88, v88, v175
	v_sub_f32_e32 v89, v89, v175
	v_sub_f32_e32 v90, v90, v175
	v_sub_f32_e32 v91, v91, v175
	v_sub_f32_e32 v92, v92, v175
	v_sub_f32_e32 v93, v93, v175
	v_sub_f32_e32 v94, v94, v175
	v_sub_f32_e32 v95, v95, v175
	v_exp_f32_e32 v88, v88
	v_exp_f32_e32 v89, v89
	v_exp_f32_e32 v90, v90
	v_exp_f32_e32 v91, v91
	v_exp_f32_e32 v92, v92
	v_exp_f32_e32 v93, v93
	v_exp_f32_e32 v94, v94
	v_exp_f32_e32 v95, v95
	v_add_f32_e32 v190, v190, v88
	v_add_f32_e32 v191, v191, v89
	v_add_f32_e32 v190, v190, v90
	v_add_f32_e32 v191, v191, v91
	v_add_f32_e32 v190, v190, v92
	v_add_f32_e32 v191, v191, v93
	v_add_f32_e32 v190, v190, v94
	v_add_f32_e32 v191, v191, v95
	v_cvt_pk_bf16_f32 v156, v88, v89
	v_cvt_pk_bf16_f32 v157, v90, v91
	v_cvt_pk_bf16_f32 v158, v92, v93
	v_cvt_pk_bf16_f32 v159, v94, v95
	v_add_f32_e32 v190, v190, v191
	v_fma_f32 v167, v167, v174, v190
	s_cbranch_vccz .Lattn_noresc_t0
	s_nop 7
	s_nop 7
	v_pk_mul_f32 v[0:1], v[0:1], v[174:175] op_sel_hi:[1,0]
	v_pk_mul_f32 v[2:3], v[2:3], v[174:175] op_sel_hi:[1,0]
	v_pk_mul_f32 v[4:5], v[4:5], v[174:175] op_sel_hi:[1,0]
	v_pk_mul_f32 v[6:7], v[6:7], v[174:175] op_sel_hi:[1,0]
	v_pk_mul_f32 v[8:9], v[8:9], v[174:175] op_sel_hi:[1,0]
	v_pk_mul_f32 v[10:11], v[10:11], v[174:175] op_sel_hi:[1,0]
	v_pk_mul_f32 v[12:13], v[12:13], v[174:175] op_sel_hi:[1,0]
	v_pk_mul_f32 v[14:15], v[14:15], v[174:175] op_sel_hi:[1,0]
	v_pk_mul_f32 v[16:17], v[16:17], v[174:175] op_sel_hi:[1,0]
	v_pk_mul_f32 v[18:19], v[18:19], v[174:175] op_sel_hi:[1,0]
	v_pk_mul_f32 v[20:21], v[20:21], v[174:175] op_sel_hi:[1,0]
	v_pk_mul_f32 v[22:23], v[22:23], v[174:175] op_sel_hi:[1,0]
	v_pk_mul_f32 v[24:25], v[24:25], v[174:175] op_sel_hi:[1,0]
	v_pk_mul_f32 v[26:27], v[26:27], v[174:175] op_sel_hi:[1,0]
	v_pk_mul_f32 v[28:29], v[28:29], v[174:175] op_sel_hi:[1,0]
	v_pk_mul_f32 v[30:31], v[30:31], v[174:175] op_sel_hi:[1,0]
	v_pk_mul_f32 v[32:33], v[32:33], v[174:175] op_sel_hi:[1,0]
	v_pk_mul_f32 v[34:35], v[34:35], v[174:175] op_sel_hi:[1,0]
	v_pk_mul_f32 v[36:37], v[36:37], v[174:175] op_sel_hi:[1,0]
	v_pk_mul_f32 v[38:39], v[38:39], v[174:175] op_sel_hi:[1,0]
	v_pk_mul_f32 v[40:41], v[40:41], v[174:175] op_sel_hi:[1,0]
	v_pk_mul_f32 v[42:43], v[42:43], v[174:175] op_sel_hi:[1,0]
	v_pk_mul_f32 v[44:45], v[44:45], v[174:175] op_sel_hi:[1,0]
	v_pk_mul_f32 v[46:47], v[46:47], v[174:175] op_sel_hi:[1,0]
	v_pk_mul_f32 v[48:49], v[48:49], v[174:175] op_sel_hi:[1,0]
	v_pk_mul_f32 v[50:51], v[50:51], v[174:175] op_sel_hi:[1,0]
	v_pk_mul_f32 v[52:53], v[52:53], v[174:175] op_sel_hi:[1,0]
	v_pk_mul_f32 v[54:55], v[54:55], v[174:175] op_sel_hi:[1,0]
	v_pk_mul_f32 v[56:57], v[56:57], v[174:175] op_sel_hi:[1,0]
	v_pk_mul_f32 v[58:59], v[58:59], v[174:175] op_sel_hi:[1,0]
	v_pk_mul_f32 v[60:61], v[60:61], v[174:175] op_sel_hi:[1,0]
	v_pk_mul_f32 v[62:63], v[62:63], v[174:175] op_sel_hi:[1,0]
	s_nop 1

.Lattn_loop_s:
	s_waitcnt vmcnt(4)
	s_barrier
	s_waitcnt lgkmcnt(5)
	v_mfma_f32_32x32x16_bf16 v[48:63], v[216:219], v[144:147], v[48:63]
	ds_read_b128 v[216:219], v188 offset:8192
	s_add_i32 s2, s42, 3
	v_max3_f32 v254, v96, v97, v98
	s_and_b32 s2, s2, 31
	v_max3_f32 v255, v112, v113, v114
	s_mul_i32 s2, s2, 0x44000
	v_max3_f32 v254, v254, v99, v100
	s_add_i32 m0, s5, 0
	v_max3_f32 v255, v255, v115, v116
	s_waitcnt lgkmcnt(5)
	v_mfma_f32_32x32x16_bf16 v[32:47], v[220:223], v[144:147], v[32:47]
	ds_read_b128 v[220:223], v188 offset:12288
	s_add_u32 s40, s26, s2
	v_max3_f32 v254, v254, v101, v102
	s_addc_u32 s41, s27, 0
	v_max3_f32 v255, v255, v117, v118
	global_load_lds_dwordx4 v170, s[40:41]
	v_max3_f32 v254, v254, v103, v104
	s_add_i32 m0, s5, 8192
	v_max3_f32 v255, v255, v119, v120
	s_waitcnt lgkmcnt(5)
	v_mfma_f32_32x32x16_bf16 v[16:31], v[224:227], v[144:147], v[16:31]
	ds_read_b128 v[224:227], v186 offset:0
	s_add_u32 s40, s40, 0x80
	v_max3_f32 v254, v254, v105, v106
	s_addc_u32 s41, s41, 0
	v_max3_f32 v255, v255, v121, v122
	global_load_lds_dwordx4 v170, s[40:41]
	v_max3_f32 v254, v254, v107, v108
	s_add_i32 s2, s42, 2
	v_max3_f32 v255, v255, v123, v124
	s_waitcnt lgkmcnt(5)
	v_mfma_f32_32x32x16_bf16 v[0:15], v[228:231], v[144:147], v[0:15]
	ds_read_b128 v[228:231], v186 offset:4096
	s_and_b32 s2, s2, 31
	v_max3_f32 v254, v254, v109, v110
	s_lshl_b32 s2, s2, 7
	v_max3_f32 v255, v255, v125, v126
	s_add_i32 m0, s5, 114688
	v_max3_f32 v254, v254, v111, v127
	s_add_u32 s44, s10, s2
	v_max_f32_e32 v254, v254, v255
	s_waitcnt lgkmcnt(5)
	v_mfma_f32_32x32x16_bf16 v[48:63], v[208:211], v[148:151], v[48:63]
	ds_read_b128 v[208:211], v186 offset:8192
	v_cmp_lt_f32_e32 vcc, 0x4138aa3b, v254
	s_addc_u32 s45, s11, 0
	global_load_lds_dwordx4 v172, s[44:45]
	s_add_i32 m0, s5, 122880
	s_add_u32 s44, s44, 0x204000
	s_addc_u32 s45, s45, 0
	global_load_lds_dwordx4 v172, s[44:45]

.Lattn_noresc_L0:
	s_waitcnt vmcnt(4)
	s_barrier
	s_waitcnt lgkmcnt(5)
	v_mfma_f32_32x32x16_bf16 v[48:63], v[216:219], v[144:147], v[48:63]
	ds_read_b128 v[216:219], v188 offset:24576
	s_add_i32 s2, s42, 4
	v_max3_f32 v254, v64, v65, v66
	s_and_b32 s2, s2, 31
	v_max3_f32 v255, v80, v81, v82
	s_mul_i32 s2, s2, 0x44000
	v_max3_f32 v254, v254, v67, v68
	s_add_i32 m0, s5, 16384
	v_max3_f32 v255, v255, v83, v84
	s_waitcnt lgkmcnt(5)
	v_mfma_f32_32x32x16_bf16 v[32:47], v[220:223], v[144:147], v[32:47]
	ds_read_b128 v[220:223], v188 offset:28672
	s_add_u32 s40, s26, s2
	v_max3_f32 v254, v254, v69, v70
	s_addc_u32 s41, s27, 0
	v_max3_f32 v255, v255, v85, v86
	global_load_lds_dwordx4 v170, s[40:41]
	v_max3_f32 v254, v254, v71, v72
	s_add_i32 m0, s5, 24576
	v_max3_f32 v255, v255, v87, v88
	s_waitcnt lgkmcnt(5)
	v_mfma_f32_32x32x16_bf16 v[16:31], v[224:227], v[144:147], v[16:31]
	ds_read_b128 v[224:227], v186 offset:16384
	s_add_u32 s40, s40, 0x80
	v_max3_f32 v254, v254, v73, v74
	s_addc_u32 s41, s41, 0
	v_max3_f32 v255, v255, v89, v90
	global_load_lds_dwordx4 v170, s[40:41]
	v_max3_f32 v254, v254, v75, v76
	s_add_i32 s2, s42, 3
	v_max3_f32 v255, v255, v91, v92
	s_waitcnt lgkmcnt(5)
	v_mfma_f32_32x32x16_bf16 v[0:15], v[228:231], v[144:147], v[0:15]
	ds_read_b128 v[228:231], v186 offset:20480
	s_and_b32 s2, s2, 31
	v_max3_f32 v254, v254, v77, v78
	s_lshl_b32 s2, s2, 7
	v_max3_f32 v255, v255, v93, v94
	s_add_i32 m0, s5, 65536
	v_max3_f32 v254, v254, v79, v95
	s_add_u32 s44, s10, s2
	v_max_f32_e32 v254, v254, v255
	s_waitcnt lgkmcnt(5)
	v_mfma_f32_32x32x16_bf16 v[48:63], v[208:211], v[148:151], v[48:63]
	ds_read_b128 v[208:211], v186 offset:24576
	v_cmp_lt_f32_e32 vcc, 0x4138aa3b, v254
	s_addc_u32 s45, s11, 0
	global_load_lds_dwordx4 v172, s[44:45]
	s_add_i32 m0, s5, 73728
	s_add_u32 s44, s44, 0x204000
	s_addc_u32 s45, s45, 0
	global_load_lds_dwordx4 v172, s[44:45]

.Lattn_noresc_L1:
	s_waitcnt vmcnt(4)
	s_barrier
	s_waitcnt lgkmcnt(5)
	v_mfma_f32_32x32x16_bf16 v[48:63], v[216:219], v[144:147], v[48:63]
	ds_read_b128 v[216:219], v188 offset:40960
	s_add_i32 s2, s42, 5
	v_max3_f32 v254, v96, v97, v98
	s_and_b32 s2, s2, 31
	v_max3_f32 v255, v112, v113, v114
	s_mul_i32 s2, s2, 0x44000
	v_max3_f32 v254, v254, v99, v100
	s_add_i32 m0, s5, 32768
	v_max3_f32 v255, v255, v115, v116
	s_waitcnt lgkmcnt(5)
	v_mfma_f32_32x32x16_bf16 v[32:47], v[220:223], v[144:147], v[32:47]
	ds_read_b128 v[220:223], v188 offset:45056
	s_add_u32 s40, s26, s2
	v_max3_f32 v254, v254, v101, v102
	s_addc_u32 s41, s27, 0
	v_max3_f32 v255, v255, v117, v118
	global_load_lds_dwordx4 v170, s[40:41]
	v_max3_f32 v254, v254, v103, v104
	s_add_i32 m0, s5, 40960
	v_max3_f32 v255, v255, v119, v120
	s_waitcnt lgkmcnt(5)
	v_mfma_f32_32x32x16_bf16 v[16:31], v[224:227], v[144:147], v[16:31]
	ds_read_b128 v[224:227], v186 offset:32768
	s_add_u32 s40, s40, 0x80
	v_max3_f32 v254, v254, v105, v106
	s_addc_u32 s41, s41, 0
	v_max3_f32 v255, v255, v121, v122
	global_load_lds_dwordx4 v170, s[40:41]
	v_max3_f32 v254, v254, v107, v108
	s_add_i32 s2, s42, 4
	v_max3_f32 v255, v255, v123, v124
	s_waitcnt lgkmcnt(5)
	v_mfma_f32_32x32x16_bf16 v[0:15], v[228:231], v[144:147], v[0:15]
	ds_read_b128 v[228:231], v186 offset:36864
	s_and_b32 s2, s2, 31
	v_max3_f32 v254, v254, v109, v110
	s_lshl_b32 s2, s2, 7
	v_max3_f32 v255, v255, v125, v126
	s_add_i32 m0, s5, 81920
	v_max3_f32 v254, v254, v111, v127
	s_add_u32 s44, s10, s2
	v_max_f32_e32 v254, v254, v255
	s_waitcnt lgkmcnt(5)
	v_mfma_f32_32x32x16_bf16 v[48:63], v[208:211], v[148:151], v[48:63]
	ds_read_b128 v[208:211], v186 offset:40960
	v_cmp_lt_f32_e32 vcc, 0x4138aa3b, v254
	s_addc_u32 s45, s11, 0
	global_load_lds_dwordx4 v172, s[44:45]
	s_add_i32 m0, s5, 90112
	s_add_u32 s44, s44, 0x204000
	s_addc_u32 s45, s45, 0
	global_load_lds_dwordx4 v172, s[44:45]

.Lattn_noresc_L2:
	s_waitcnt vmcnt(4)
	s_barrier
	s_waitcnt lgkmcnt(5)
	v_mfma_f32_32x32x16_bf16 v[48:63], v[216:219], v[144:147], v[48:63]
	ds_read_b128 v[216:219], v188 offset:57344
	s_add_i32 s2, s42, 6
	v_max3_f32 v254, v64, v65, v66
	s_and_b32 s2, s2, 31
	v_max3_f32 v255, v80, v81, v82
	s_mul_i32 s2, s2, 0x44000
	v_max3_f32 v254, v254, v67, v68
	s_add_i32 m0, s5, 49152
	v_max3_f32 v255, v255, v83, v84
	s_waitcnt lgkmcnt(5)
	v_mfma_f32_32x32x16_bf16 v[32:47], v[220:223], v[144:147], v[32:47]
	ds_read_b128 v[220:223], v188 offset:61440
	s_add_u32 s40, s26, s2
	v_max3_f32 v254, v254, v69, v70
	s_addc_u32 s41, s27, 0
	v_max3_f32 v255, v255, v85, v86
	global_load_lds_dwordx4 v170, s[40:41]
	v_max3_f32 v254, v254, v71, v72
	s_add_i32 m0, s5, 57344
	v_max3_f32 v255, v255, v87, v88
	s_waitcnt lgkmcnt(5)
	v_mfma_f32_32x32x16_bf16 v[16:31], v[224:227], v[144:147], v[16:31]
	ds_read_b128 v[224:227], v186 offset:49152
	s_add_u32 s40, s40, 0x80
	v_max3_f32 v254, v254, v73, v74
	s_addc_u32 s41, s41, 0
	v_max3_f32 v255, v255, v89, v90
	global_load_lds_dwordx4 v170, s[40:41]
	v_max3_f32 v254, v254, v75, v76
	s_add_i32 s2, s42, 5
	v_max3_f32 v255, v255, v91, v92
	s_waitcnt lgkmcnt(5)
	v_mfma_f32_32x32x16_bf16 v[0:15], v[228:231], v[144:147], v[0:15]
	ds_read_b128 v[228:231], v186 offset:53248
	s_and_b32 s2, s2, 31
	v_max3_f32 v254, v254, v77, v78
	s_lshl_b32 s2, s2, 7
	v_max3_f32 v255, v255, v93, v94
	s_add_i32 m0, s5, 98304
	v_max3_f32 v254, v254, v79, v95
	s_add_u32 s44, s10, s2
	v_max_f32_e32 v254, v254, v255
	s_waitcnt lgkmcnt(5)
	v_mfma_f32_32x32x16_bf16 v[48:63], v[208:211], v[148:151], v[48:63]
	ds_read_b128 v[208:211], v186 offset:57344
	v_cmp_lt_f32_e32 vcc, 0x4138aa3b, v254
	s_addc_u32 s45, s11, 0
	global_load_lds_dwordx4 v172, s[44:45]
	s_add_i32 m0, s5, 106496
	s_add_u32 s44, s44, 0x204000
	s_addc_u32 s45, s45, 0
	global_load_lds_dwordx4 v172, s[44:45]

.Lattn_noresc_L3:
	s_add_i32 s42, s42, 4
	s_add_i32 s47, s47, -1
	s_cmp_lg_u32 s47, 0
	s_cbranch_scc1 .Lattn_loop_s
	s_waitcnt vmcnt(4)
	s_barrier
	s_waitcnt lgkmcnt(5)
	v_mfma_f32_32x32x16_bf16 v[48:63], v[216:219], v[144:147], v[48:63]
	ds_read_b128 v[216:219], v188 offset:8192
	s_nop 3
	s_add_i32 s2, s42, 2
	v_max3_f32 v254, v96, v97, v98
	s_and_b32 s2, s2, 31
	v_max3_f32 v255, v112, v113, v114
	s_lshl_b32 s2, s2, 7
	v_max3_f32 v254, v254, v99, v100
	s_add_i32 m0, s5, 114688
	s_waitcnt lgkmcnt(5)
	v_mfma_f32_32x32x16_bf16 v[32:47], v[220:223], v[144:147], v[32:47]
	ds_read_b128 v[220:223], v188 offset:12288
	v_max3_f32 v255, v255, v115, v116
	s_add_u32 s44, s10, s2
	v_max3_f32 v254, v254, v101, v102
	v_max3_f32 v255, v255, v117, v118
	v_max3_f32 v254, v254, v103, v104
	v_max3_f32 v255, v255, v119, v120
	v_max3_f32 v254, v254, v105, v106
	v_max3_f32 v255, v255, v121, v122
	s_waitcnt lgkmcnt(5)
	v_mfma_f32_32x32x16_bf16 v[16:31], v[224:227], v[144:147], v[16:31]
	ds_read_b128 v[224:227], v186 offset:0
	v_max3_f32 v254, v254, v107, v108
	v_max3_f32 v255, v255, v123, v124
	v_max3_f32 v254, v254, v109, v110
	v_max3_f32 v255, v255, v125, v126
	v_max3_f32 v254, v254, v111, v127
	v_max_f32_e32 v254, v254, v255
	v_cmp_lt_f32_e32 vcc, 0x4138aa3b, v254
	s_addc_u32 s45, s11, 0
	s_waitcnt lgkmcnt(5)
	v_mfma_f32_32x32x16_bf16 v[0:15], v[228:231], v[144:147], v[0:15]
	ds_read_b128 v[228:231], v186 offset:4096
	global_load_lds_dwordx4 v172, s[44:45]
	s_add_i32 m0, s5, 122880
	s_add_u32 s44, s44, 0x204000
	s_addc_u32 s45, s45, 0
	global_load_lds_dwordx4 v172, s[44:45]
